# de-serialised gain-folded weight transposes: 16 (W,gain) load pairs in flight per wait instead of one
# speedup vs baseline: 1.0076x; 1.0076x over previous
; __device__ __forceinline__ void transpose_mat(const float* __restrict__ W, int K, int N, int Npad, bf16_t* __restrict__ WT, int blk_mul, int blk_off,
;                                               LAS float* scr, int gw, int NGW, int lane, const float* __restrict__ gk = nullptr) {
;     ...
;         const int kb = it / nblk, nb = it % nblk, k0 = 64 * kb, n0 = 32 * nb;
;         const int ncol = n0 + (lane & 31);
; #pragma unroll
;         for (int i = 0; i < 32; ++i) { const int kk = 2 * i + (lane >> 5); float w = (ncol < N) ? W[(size_t)(k0 + kk) * N + ncol] : 0.f; if (gk) w *= gk[k0 + kk]; scr[kk * 33 + (lane & 31)] = w; }
; __device__ __forceinline__ void convert_layer(int l, const float* w_gate, const float* w_up, const float* w_down, const float* ffn_g, const float* w_in, const float* mix_g, ...
;     ...
;         transpose_mat(w_gate + wo, DM, FF, FF, (bf16_t*)(ws + WS_WGU + lf * SZ_WGU), 256, 0, scr, gw, NGW, lane, ffn_g + (size_t)lf * DM);
;         transpose_mat(w_up + wo, DM, FF, FF, (bf16_t*)(ws + WS_WGU + lf * SZ_WGU), 256, 128, scr, gw, NGW, lane, ffn_g + (size_t)lf * DM);
.LBB0_7:
	s_mul_hi_i32 s2, s66, 0x2e8ba2e9
	s_lshr_b32 s3, s2, 31
	s_ashr_i32 s67, s2, 4
	s_add_i32 s67, s67, s3
	s_mul_i32 s68, s67, 0xfffff500
	s_add_i32 s2, s68, s45
	v_add_u32_e32 v12, s2, v6
	s_lshl_b32 s52, s67, 6
	v_ashrrev_i32_e32 v13, 31, v12
	v_cmp_gt_i32_e64 s[2:3], s59, v12
	v_lshl_add_u64 v[12:13], v[12:13], 2, s[50:51]
	v_mov_b32_e32 v136, 0
	v_or_b32_e32 v14, s52, v2
	s_and_saveexec_b64 s[4:5], s[2:3]
	s_cbranch_execz .LBB0_9
	v_mad_i64_i32 v[82:83], s[54:55], v14, s60, v[12:13]
	global_load_dword v136, v[82:83], off
.LBB0_9:
	s_or_b64 exec, exec, s[4:5]
	v_cndmask_b32_e64 v15, 0, 1, s[40:41]
	v_cmp_ne_u32_e64 s[4:5], 1, v15
	s_andn2_b64 vcc, exec, s[40:41]
	s_cbranch_vccnz .LBB0_11
	v_ashrrev_i32_e32 v15, 31, v14
	v_lshl_add_u64 v[14:15], v[14:15], 2, s[46:47]
	global_load_dword v168, v[14:15], off
.LBB0_11:
	v_mov_b32_e32 v137, 0
	s_and_saveexec_b64 s[54:55], s[2:3]
	s_cbranch_execz .LBB0_13
	v_or_b32_e32 v14, s52, v19
	v_mad_i64_i32 v[14:15], s[70:71], v14, s60, v[12:13]
	global_load_dword v137, v[14:15], off
.LBB0_13:
	s_or_b64 exec, exec, s[54:55]
	s_and_b64 vcc, exec, s[4:5]
	s_cbranch_vccnz .LBB0_15
	s_ashr_i32 s53, s52, 31
	v_lshl_add_u64 v[82:83], s[52:53], 0, v[2:3]
	v_lshl_add_u64 v[82:83], v[82:83], 2, s[46:47]
	global_load_dword v169, v[82:83], off offset:8
.LBB0_15:
	v_mov_b32_e32 v138, 0
	s_and_saveexec_b64 s[54:55], s[2:3]
	s_cbranch_execz .LBB0_17
	v_or_b32_e32 v14, s52, v20
	v_mad_i64_i32 v[14:15], s[70:71], v14, s60, v[12:13]
	global_load_dword v138, v[14:15], off
.LBB0_17:
	s_or_b64 exec, exec, s[54:55]
	s_and_b64 vcc, exec, s[4:5]
	s_cbranch_vccnz .LBB0_19
	s_ashr_i32 s53, s52, 31
	v_lshl_add_u64 v[82:83], s[52:53], 0, v[2:3]
	v_lshl_add_u64 v[82:83], v[82:83], 2, s[46:47]
	global_load_dword v170, v[82:83], off offset:16
.LBB0_19:
	v_mov_b32_e32 v139, 0
	s_and_saveexec_b64 s[54:55], s[2:3]
	s_cbranch_execz .LBB0_21
	v_or_b32_e32 v14, s52, v21
	v_mad_i64_i32 v[14:15], s[70:71], v14, s60, v[12:13]
	global_load_dword v139, v[14:15], off
.LBB0_21:
	s_or_b64 exec, exec, s[54:55]
	s_and_b64 vcc, exec, s[4:5]
	s_cbranch_vccnz .LBB0_23
	s_ashr_i32 s53, s52, 31
	v_lshl_add_u64 v[82:83], s[52:53], 0, v[2:3]
	v_lshl_add_u64 v[82:83], v[82:83], 2, s[46:47]
	global_load_dword v171, v[82:83], off offset:24
.LBB0_23:
	v_mov_b32_e32 v140, 0
	s_and_saveexec_b64 s[54:55], s[2:3]
	s_cbranch_execz .LBB0_25
	v_or_b32_e32 v14, s52, v22
	v_mad_i64_i32 v[14:15], s[70:71], v14, s60, v[12:13]
	global_load_dword v140, v[14:15], off
.LBB0_25:
	s_or_b64 exec, exec, s[54:55]
	s_and_b64 vcc, exec, s[4:5]
	s_cbranch_vccnz .LBB0_27
	s_ashr_i32 s53, s52, 31
	v_lshl_add_u64 v[82:83], s[52:53], 0, v[2:3]
	v_lshl_add_u64 v[82:83], v[82:83], 2, s[46:47]
	global_load_dword v172, v[82:83], off offset:32
.LBB0_27:
	v_mov_b32_e32 v141, 0
	s_and_saveexec_b64 s[54:55], s[2:3]
	s_cbranch_execz .LBB0_29
	v_or_b32_e32 v14, s52, v23
	v_mad_i64_i32 v[14:15], s[70:71], v14, s60, v[12:13]
	global_load_dword v141, v[14:15], off
.LBB0_29:
	s_or_b64 exec, exec, s[54:55]
	s_and_b64 vcc, exec, s[4:5]
	s_cbranch_vccnz .LBB0_31
	s_ashr_i32 s53, s52, 31
	v_lshl_add_u64 v[82:83], s[52:53], 0, v[2:3]
	v_lshl_add_u64 v[82:83], v[82:83], 2, s[46:47]
	global_load_dword v173, v[82:83], off offset:40
.LBB0_31:
	v_mov_b32_e32 v142, 0
	s_and_saveexec_b64 s[54:55], s[2:3]
	s_cbranch_execz .LBB0_33
	v_or_b32_e32 v14, s52, v24
	v_mad_i64_i32 v[14:15], s[70:71], v14, s60, v[12:13]
	global_load_dword v142, v[14:15], off
.LBB0_33:
	s_or_b64 exec, exec, s[54:55]
	s_and_b64 vcc, exec, s[4:5]
	s_cbranch_vccnz .LBB0_35
	s_ashr_i32 s53, s52, 31
	v_lshl_add_u64 v[82:83], s[52:53], 0, v[2:3]
	v_lshl_add_u64 v[82:83], v[82:83], 2, s[46:47]
	global_load_dword v174, v[82:83], off offset:48
.LBB0_35:
	v_mov_b32_e32 v143, 0
	s_and_saveexec_b64 s[54:55], s[2:3]
	s_cbranch_execz .LBB0_37
	v_or_b32_e32 v14, s52, v25
	v_mad_i64_i32 v[14:15], s[70:71], v14, s60, v[12:13]
	global_load_dword v143, v[14:15], off
.LBB0_37:
	s_or_b64 exec, exec, s[54:55]
	s_and_b64 vcc, exec, s[4:5]
	s_cbranch_vccnz .LBB0_39
	s_ashr_i32 s53, s52, 31
	v_lshl_add_u64 v[82:83], s[52:53], 0, v[2:3]
	v_lshl_add_u64 v[82:83], v[82:83], 2, s[46:47]
	global_load_dword v175, v[82:83], off offset:56
.LBB0_39:
	v_mov_b32_e32 v144, 0
	s_and_saveexec_b64 s[54:55], s[2:3]
	s_cbranch_execz .LBB0_41
	v_or_b32_e32 v14, s52, v27
	v_mad_i64_i32 v[14:15], s[70:71], v14, s60, v[12:13]
	global_load_dword v144, v[14:15], off
.LBB0_41:
	s_or_b64 exec, exec, s[54:55]
	s_and_b64 vcc, exec, s[4:5]
	s_cbranch_vccnz .LBB0_43
	s_ashr_i32 s53, s52, 31
	v_lshl_add_u64 v[82:83], s[52:53], 0, v[2:3]
	v_lshl_add_u64 v[82:83], v[82:83], 2, s[46:47]
	global_load_dword v176, v[82:83], off offset:64
.LBB0_43:
	v_mov_b32_e32 v145, 0
	s_and_saveexec_b64 s[54:55], s[2:3]
	s_cbranch_execz .LBB0_45
	v_or_b32_e32 v14, s52, v28
	v_mad_i64_i32 v[14:15], s[70:71], v14, s60, v[12:13]
	global_load_dword v145, v[14:15], off
.LBB0_45:
	s_or_b64 exec, exec, s[54:55]
	s_and_b64 vcc, exec, s[4:5]
	s_cbranch_vccnz .LBB0_47
	s_ashr_i32 s53, s52, 31
	v_lshl_add_u64 v[82:83], s[52:53], 0, v[2:3]
	v_lshl_add_u64 v[82:83], v[82:83], 2, s[46:47]
	global_load_dword v177, v[82:83], off offset:72
.LBB0_47:
	v_mov_b32_e32 v146, 0
	s_and_saveexec_b64 s[54:55], s[2:3]
	s_cbranch_execz .LBB0_49
	v_or_b32_e32 v14, s52, v29
	v_mad_i64_i32 v[14:15], s[70:71], v14, s60, v[12:13]
	global_load_dword v146, v[14:15], off
.LBB0_49:
	s_or_b64 exec, exec, s[54:55]
	s_and_b64 vcc, exec, s[4:5]
	s_cbranch_vccnz .LBB0_51
	s_ashr_i32 s53, s52, 31
	v_lshl_add_u64 v[82:83], s[52:53], 0, v[2:3]
	v_lshl_add_u64 v[82:83], v[82:83], 2, s[46:47]
	global_load_dword v178, v[82:83], off offset:80
; #define LDS_WAIT() asm volatile("s_waitcnt lgkmcnt(0)" ::: "memory")
; __device__ __forceinline__ void transpose_mat(const float* __restrict__ W, int K, int N, int Npad, bf16_t* __restrict__ WT, int blk_mul, int blk_off,
;                                               LAS float* scr, int gw, int NGW, int lane, const float* __restrict__ gk = nullptr) {
;     ...
;         const int kb = it / nblk, nb = it % nblk, k0 = 64 * kb, n0 = 32 * nb;
;         const int ncol = n0 + (lane & 31);
; #pragma unroll
;         for (int i = 0; i < 32; ++i) { const int kk = 2 * i + (lane >> 5); float w = (ncol < N) ? W[(size_t)(k0 + kk) * N + ncol] : 0.f; if (gk) w *= gk[k0 + kk]; scr[kk * 33 + (lane & 31)] = w; }
;         LDS_WAIT();
.LBB0_51:
	v_mov_b32_e32 v147, 0
	s_and_saveexec_b64 s[54:55], s[2:3]
	s_cbranch_execz .LBB0_53
	v_or_b32_e32 v14, s52, v30
	v_mad_i64_i32 v[14:15], s[70:71], v14, s60, v[12:13]
	global_load_dword v147, v[14:15], off
.LBB0_53:
	s_or_b64 exec, exec, s[54:55]
	s_and_b64 vcc, exec, s[4:5]
	s_cbranch_vccnz .LBB0_55
	s_ashr_i32 s53, s52, 31
	v_lshl_add_u64 v[82:83], s[52:53], 0, v[2:3]
	v_lshl_add_u64 v[82:83], v[82:83], 2, s[46:47]
	global_load_dword v179, v[82:83], off offset:88
.LBB0_55:
	v_mov_b32_e32 v148, 0
	s_and_saveexec_b64 s[54:55], s[2:3]
	s_cbranch_execz .LBB0_57
	v_or_b32_e32 v14, s52, v31
	v_mad_i64_i32 v[14:15], s[70:71], v14, s60, v[12:13]
	global_load_dword v148, v[14:15], off
.LBB0_57:
	s_or_b64 exec, exec, s[54:55]
	s_and_b64 vcc, exec, s[4:5]
	s_cbranch_vccnz .LBB0_59
	s_ashr_i32 s53, s52, 31
	v_lshl_add_u64 v[82:83], s[52:53], 0, v[2:3]
	v_lshl_add_u64 v[82:83], v[82:83], 2, s[46:47]
	global_load_dword v180, v[82:83], off offset:96
.LBB0_59:
	v_mov_b32_e32 v149, 0
	s_and_saveexec_b64 s[54:55], s[2:3]
	s_cbranch_execz .LBB0_61
	v_or_b32_e32 v14, s52, v32
	v_mad_i64_i32 v[14:15], s[70:71], v14, s60, v[12:13]
	global_load_dword v149, v[14:15], off
.LBB0_61:
	s_or_b64 exec, exec, s[54:55]
	s_and_b64 vcc, exec, s[4:5]
	s_cbranch_vccnz .LBB0_63
	s_ashr_i32 s53, s52, 31
	v_lshl_add_u64 v[82:83], s[52:53], 0, v[2:3]
	v_lshl_add_u64 v[82:83], v[82:83], 2, s[46:47]
	global_load_dword v181, v[82:83], off offset:104
.LBB0_63:
	v_mov_b32_e32 v150, 0
	s_and_saveexec_b64 s[54:55], s[2:3]
	s_cbranch_execz .LBB0_65
	v_or_b32_e32 v14, s52, v33
	v_mad_i64_i32 v[14:15], s[70:71], v14, s60, v[12:13]
	global_load_dword v150, v[14:15], off
.LBB0_65:
	s_or_b64 exec, exec, s[54:55]
	s_and_b64 vcc, exec, s[4:5]
	s_cbranch_vccnz .LBB0_67
	s_ashr_i32 s53, s52, 31
	v_lshl_add_u64 v[82:83], s[52:53], 0, v[2:3]
	v_lshl_add_u64 v[82:83], v[82:83], 2, s[46:47]
	global_load_dword v182, v[82:83], off offset:112
.LBB0_67:
	v_mov_b32_e32 v151, 0
	s_and_saveexec_b64 s[54:55], s[2:3]
	s_cbranch_execz .LBB0_69
	v_or_b32_e32 v14, s52, v34
	v_mad_i64_i32 v[14:15], s[70:71], v14, s60, v[12:13]
	global_load_dword v151, v[14:15], off
.LBB0_69:
	s_or_b64 exec, exec, s[54:55]
	s_and_b64 vcc, exec, s[4:5]
	s_cbranch_vccnz .LBB0_71
	s_ashr_i32 s53, s52, 31
	v_lshl_add_u64 v[82:83], s[52:53], 0, v[2:3]
	v_lshl_add_u64 v[82:83], v[82:83], 2, s[46:47]
	global_load_dword v183, v[82:83], off offset:120
.LBB0_71:
	s_waitcnt vmcnt(0)
	s_and_b64 vcc, exec, s[4:5]
	s_cbranch_vccnz .Ltp0_nomul_1
	v_mul_f32_e32 v136, v136, v168
	v_mul_f32_e32 v137, v137, v169
	v_mul_f32_e32 v138, v138, v170
	v_mul_f32_e32 v139, v139, v171
	v_mul_f32_e32 v140, v140, v172
	v_mul_f32_e32 v141, v141, v173
	v_mul_f32_e32 v142, v142, v174
	v_mul_f32_e32 v143, v143, v175
	v_mul_f32_e32 v144, v144, v176
	v_mul_f32_e32 v145, v145, v177
	v_mul_f32_e32 v146, v146, v178
	v_mul_f32_e32 v147, v147, v179
	v_mul_f32_e32 v148, v148, v180
	v_mul_f32_e32 v149, v149, v181
	v_mul_f32_e32 v150, v150, v182
	v_mul_f32_e32 v151, v151, v183
.Ltp0_nomul_1:
	v_add_u32_e32 v14, v51, v5
	ds_write_b32 v14, v136
	v_add_u32_e32 v15, v51, v69
	ds_write_b32 v15, v137
	v_add_u32_e32 v15, v51, v70
	ds_write_b32 v15, v138
	v_add_u32_e32 v15, v51, v71
	ds_write_b32 v15, v139
	v_add_u32_e32 v15, v51, v68
	ds_write_b32 v15, v140
	v_add_u32_e32 v15, v51, v72
	ds_write_b32 v15, v141
	v_add_u32_e32 v15, v51, v73
	ds_write_b32 v15, v142
	v_add_u32_e32 v15, v51, v74
	ds_write_b32 v15, v143
	v_add_u32_e32 v15, v51, v78
	ds_write_b32 v15, v144
	v_add_u32_e32 v15, v51, v75
	ds_write_b32 v15, v145
	v_add_u32_e32 v15, v51, v76
	ds_write_b32 v15, v146
	v_add_u32_e32 v15, v51, v77
	ds_write_b32 v15, v147
	v_add_u32_e32 v15, v51, v55
	ds_write_b32 v15, v148
	v_add_u32_e32 v15, v51, v57
	ds_write_b32 v15, v149
	v_add_u32_e32 v15, v51, v58
	ds_write_b32 v15, v150
	v_add_u32_e32 v15, v51, v59
	ds_write_b32 v15, v151
	v_mov_b32_e32 v152, 0
	s_and_saveexec_b64 s[54:55], s[2:3]
	s_cbranch_execz .LBB0_73
	v_or_b32_e32 v14, s52, v35
	v_mad_i64_i32 v[14:15], s[70:71], v14, s60, v[12:13]
	global_load_dword v152, v[14:15], off
.LBB0_73:
	s_or_b64 exec, exec, s[54:55]
	s_and_b64 vcc, exec, s[4:5]
	s_cbranch_vccnz .LBB0_75
	s_ashr_i32 s53, s52, 31
	v_lshl_add_u64 v[82:83], s[52:53], 0, v[2:3]
	v_lshl_add_u64 v[82:83], v[82:83], 2, s[46:47]
	global_load_dword v184, v[82:83], off offset:128
.LBB0_75:
	v_mov_b32_e32 v153, 0
	s_and_saveexec_b64 s[54:55], s[2:3]
	s_cbranch_execz .LBB0_77
	v_or_b32_e32 v14, s52, v36
	v_mad_i64_i32 v[14:15], s[70:71], v14, s60, v[12:13]
	global_load_dword v153, v[14:15], off
.LBB0_77:
	s_or_b64 exec, exec, s[54:55]
	s_and_b64 vcc, exec, s[4:5]
	s_cbranch_vccnz .LBB0_79
	s_ashr_i32 s53, s52, 31
	v_lshl_add_u64 v[82:83], s[52:53], 0, v[2:3]
	v_lshl_add_u64 v[82:83], v[82:83], 2, s[46:47]
	global_load_dword v185, v[82:83], off offset:136
.LBB0_79:
	v_mov_b32_e32 v154, 0
	s_and_saveexec_b64 s[54:55], s[2:3]
	s_cbranch_execz .LBB0_81
	v_or_b32_e32 v14, s52, v37
	v_mad_i64_i32 v[14:15], s[70:71], v14, s60, v[12:13]
	global_load_dword v154, v[14:15], off
.LBB0_81:
	s_or_b64 exec, exec, s[54:55]
	s_and_b64 vcc, exec, s[4:5]
	s_cbranch_vccnz .LBB0_83
	s_ashr_i32 s53, s52, 31
	v_lshl_add_u64 v[82:83], s[52:53], 0, v[2:3]
	v_lshl_add_u64 v[82:83], v[82:83], 2, s[46:47]
	global_load_dword v186, v[82:83], off offset:144
.LBB0_83:
	v_mov_b32_e32 v155, 0
	s_and_saveexec_b64 s[54:55], s[2:3]
	s_cbranch_execz .LBB0_85
	v_or_b32_e32 v14, s52, v38
	v_mad_i64_i32 v[14:15], s[70:71], v14, s60, v[12:13]
	global_load_dword v155, v[14:15], off
; __device__ __forceinline__ void transpose_mat(const float* __restrict__ W, int K, int N, int Npad, bf16_t* __restrict__ WT, int blk_mul, int blk_off,
;                                               LAS float* scr, int gw, int NGW, int lane, const float* __restrict__ gk = nullptr) {
;     ...
;         const int kb = it / nblk, nb = it % nblk, k0 = 64 * kb, n0 = 32 * nb;
;         const int ncol = n0 + (lane & 31);
; #pragma unroll
;         for (int i = 0; i < 32; ++i) { const int kk = 2 * i + (lane >> 5); float w = (ncol < N) ? W[(size_t)(k0 + kk) * N + ncol] : 0.f; if (gk) w *= gk[k0 + kk]; scr[kk * 33 + (lane & 31)] = w; }
.LBB0_85:
	s_or_b64 exec, exec, s[54:55]
	s_and_b64 vcc, exec, s[4:5]
	s_cbranch_vccnz .LBB0_87
	s_ashr_i32 s53, s52, 31
	v_lshl_add_u64 v[82:83], s[52:53], 0, v[2:3]
	v_lshl_add_u64 v[82:83], v[82:83], 2, s[46:47]
	global_load_dword v187, v[82:83], off offset:152
.LBB0_87:
	v_mov_b32_e32 v156, 0
	s_and_saveexec_b64 s[54:55], s[2:3]
	s_cbranch_execz .LBB0_89
	v_or_b32_e32 v14, s52, v39
	v_mad_i64_i32 v[14:15], s[70:71], v14, s60, v[12:13]
	global_load_dword v156, v[14:15], off
.LBB0_89:
	s_or_b64 exec, exec, s[54:55]
	s_and_b64 vcc, exec, s[4:5]
	s_cbranch_vccnz .LBB0_91
	s_ashr_i32 s53, s52, 31
	v_lshl_add_u64 v[82:83], s[52:53], 0, v[2:3]
	v_lshl_add_u64 v[82:83], v[82:83], 2, s[46:47]
	global_load_dword v188, v[82:83], off offset:160
.LBB0_91:
	v_mov_b32_e32 v157, 0
	s_and_saveexec_b64 s[54:55], s[2:3]
	s_cbranch_execz .LBB0_93
	v_or_b32_e32 v14, s52, v40
	v_mad_i64_i32 v[14:15], s[70:71], v14, s60, v[12:13]
	global_load_dword v157, v[14:15], off
.LBB0_93:
	s_or_b64 exec, exec, s[54:55]
	s_and_b64 vcc, exec, s[4:5]
	s_cbranch_vccnz .LBB0_95
	s_ashr_i32 s53, s52, 31
	v_lshl_add_u64 v[82:83], s[52:53], 0, v[2:3]
	v_lshl_add_u64 v[82:83], v[82:83], 2, s[46:47]
	global_load_dword v189, v[82:83], off offset:168
.LBB0_95:
	v_mov_b32_e32 v158, 0
	s_and_saveexec_b64 s[54:55], s[2:3]
	s_cbranch_execz .LBB0_97
	v_or_b32_e32 v14, s52, v41
	v_mad_i64_i32 v[14:15], s[70:71], v14, s60, v[12:13]
	global_load_dword v158, v[14:15], off
.LBB0_97:
	s_or_b64 exec, exec, s[54:55]
	s_and_b64 vcc, exec, s[4:5]
	s_cbranch_vccnz .LBB0_99
	s_ashr_i32 s53, s52, 31
	v_lshl_add_u64 v[82:83], s[52:53], 0, v[2:3]
	v_lshl_add_u64 v[82:83], v[82:83], 2, s[46:47]
	global_load_dword v190, v[82:83], off offset:176
.LBB0_99:
	v_mov_b32_e32 v159, 0
	s_and_saveexec_b64 s[54:55], s[2:3]
	s_cbranch_execz .LBB0_101
	v_or_b32_e32 v14, s52, v42
	v_mad_i64_i32 v[14:15], s[70:71], v14, s60, v[12:13]
	global_load_dword v159, v[14:15], off
.LBB0_101:
	s_or_b64 exec, exec, s[54:55]
	s_and_b64 vcc, exec, s[4:5]
	s_cbranch_vccnz .LBB0_103
	s_ashr_i32 s53, s52, 31
	v_lshl_add_u64 v[82:83], s[52:53], 0, v[2:3]
	v_lshl_add_u64 v[82:83], v[82:83], 2, s[46:47]
	global_load_dword v191, v[82:83], off offset:184
.LBB0_103:
	v_mov_b32_e32 v160, 0
	s_and_saveexec_b64 s[54:55], s[2:3]
	s_cbranch_execz .LBB0_105
	v_or_b32_e32 v14, s52, v43
	v_mad_i64_i32 v[14:15], s[70:71], v14, s60, v[12:13]
	global_load_dword v160, v[14:15], off
.LBB0_105:
	s_or_b64 exec, exec, s[54:55]
	s_and_b64 vcc, exec, s[4:5]
	s_cbranch_vccnz .LBB0_107
	s_ashr_i32 s53, s52, 31
	v_lshl_add_u64 v[82:83], s[52:53], 0, v[2:3]
	v_lshl_add_u64 v[82:83], v[82:83], 2, s[46:47]
	global_load_dword v192, v[82:83], off offset:192
.LBB0_107:
	v_mov_b32_e32 v161, 0
	s_and_saveexec_b64 s[54:55], s[2:3]
	s_cbranch_execz .LBB0_109
	v_or_b32_e32 v14, s52, v44
	v_mad_i64_i32 v[14:15], s[70:71], v14, s60, v[12:13]
	global_load_dword v161, v[14:15], off
.LBB0_109:
	s_or_b64 exec, exec, s[54:55]
	s_and_b64 vcc, exec, s[4:5]
	s_cbranch_vccnz .LBB0_111
	s_ashr_i32 s53, s52, 31
	v_lshl_add_u64 v[82:83], s[52:53], 0, v[2:3]
	v_lshl_add_u64 v[82:83], v[82:83], 2, s[46:47]
	global_load_dword v193, v[82:83], off offset:200
.LBB0_111:
	v_mov_b32_e32 v162, 0
	s_and_saveexec_b64 s[54:55], s[2:3]
	s_cbranch_execz .LBB0_113
	v_or_b32_e32 v14, s52, v45
	v_mad_i64_i32 v[14:15], s[70:71], v14, s60, v[12:13]
	global_load_dword v162, v[14:15], off
.LBB0_113:
	s_or_b64 exec, exec, s[54:55]
	s_and_b64 vcc, exec, s[4:5]
	s_cbranch_vccnz .LBB0_115
	s_ashr_i32 s53, s52, 31
	v_lshl_add_u64 v[82:83], s[52:53], 0, v[2:3]
	v_lshl_add_u64 v[82:83], v[82:83], 2, s[46:47]
	global_load_dword v194, v[82:83], off offset:208
; #define LDS_WAIT() asm volatile("s_waitcnt lgkmcnt(0)" ::: "memory")
; __device__ __forceinline__ void transpose_mat(const float* __restrict__ W, int K, int N, int Npad, bf16_t* __restrict__ WT, int blk_mul, int blk_off,
;                                               LAS float* scr, int gw, int NGW, int lane, const float* __restrict__ gk = nullptr) {
;     ...
;         const int kb = it / nblk, nb = it % nblk, k0 = 64 * kb, n0 = 32 * nb;
;         const int ncol = n0 + (lane & 31);
; #pragma unroll
;         for (int i = 0; i < 32; ++i) { const int kk = 2 * i + (lane >> 5); float w = (ncol < N) ? W[(size_t)(k0 + kk) * N + ncol] : 0.f; if (gk) w *= gk[k0 + kk]; scr[kk * 33 + (lane & 31)] = w; }
;         LDS_WAIT();
.LBB0_115:
	v_mov_b32_e32 v163, 0
	s_and_saveexec_b64 s[54:55], s[2:3]
	s_cbranch_execz .LBB0_117
	v_or_b32_e32 v15, s52, v46
	v_mad_i64_i32 v[82:83], s[70:71], v15, s60, v[12:13]
	global_load_dword v163, v[82:83], off
.LBB0_117:
	s_or_b64 exec, exec, s[54:55]
	s_and_b64 vcc, exec, s[4:5]
	s_cbranch_vccnz .LBB0_119
	s_ashr_i32 s53, s52, 31
	v_lshl_add_u64 v[82:83], s[52:53], 0, v[2:3]
	v_lshl_add_u64 v[82:83], v[82:83], 2, s[46:47]
	global_load_dword v195, v[82:83], off offset:216
.LBB0_119:
	v_mov_b32_e32 v164, 0
	s_and_saveexec_b64 s[54:55], s[2:3]
	s_cbranch_execz .LBB0_121
	v_or_b32_e32 v15, s52, v47
	v_mad_i64_i32 v[82:83], s[70:71], v15, s60, v[12:13]
	global_load_dword v164, v[82:83], off
.LBB0_121:
	s_or_b64 exec, exec, s[54:55]
	s_and_b64 vcc, exec, s[4:5]
	s_cbranch_vccnz .LBB0_123
	s_ashr_i32 s53, s52, 31
	v_lshl_add_u64 v[82:83], s[52:53], 0, v[2:3]
	v_lshl_add_u64 v[82:83], v[82:83], 2, s[46:47]
	global_load_dword v196, v[82:83], off offset:224
.LBB0_123:
	v_mov_b32_e32 v165, 0
	s_and_saveexec_b64 s[54:55], s[2:3]
	s_cbranch_execz .LBB0_125
	v_or_b32_e32 v15, s52, v48
	v_mad_i64_i32 v[82:83], s[70:71], v15, s60, v[12:13]
	global_load_dword v165, v[82:83], off
.LBB0_125:
	s_or_b64 exec, exec, s[54:55]
	s_and_b64 vcc, exec, s[4:5]
	s_cbranch_vccnz .LBB0_127
	s_ashr_i32 s53, s52, 31
	v_lshl_add_u64 v[82:83], s[52:53], 0, v[2:3]
	v_lshl_add_u64 v[82:83], v[82:83], 2, s[46:47]
	global_load_dword v197, v[82:83], off offset:232
.LBB0_127:
	v_mov_b32_e32 v166, 0
	s_and_saveexec_b64 s[54:55], s[2:3]
	s_cbranch_execz .LBB0_129
	v_or_b32_e32 v15, s52, v49
	v_mad_i64_i32 v[82:83], s[70:71], v15, s60, v[12:13]
	global_load_dword v166, v[82:83], off
.LBB0_129:
	s_or_b64 exec, exec, s[54:55]
	s_and_b64 vcc, exec, s[4:5]
	s_cbranch_vccnz .LBB0_131
	s_ashr_i32 s53, s52, 31
	v_lshl_add_u64 v[82:83], s[52:53], 0, v[2:3]
	v_lshl_add_u64 v[82:83], v[82:83], 2, s[46:47]
	global_load_dword v198, v[82:83], off offset:240
.LBB0_131:
	v_mov_b32_e32 v167, 0
	s_and_saveexec_b64 s[4:5], s[2:3]
	s_cbranch_execz .LBB0_133
	v_or_b32_e32 v15, s52, v50
	v_mad_i64_i32 v[12:13], s[2:3], v15, s60, v[12:13]
	global_load_dword v167, v[12:13], off
.LBB0_133:
	s_or_b64 exec, exec, s[4:5]
	s_and_b64 vcc, exec, s[40:41]
	s_cbranch_vccz .LBB0_135
	s_ashr_i32 s53, s52, 31
	v_lshl_add_u64 v[12:13], s[52:53], 0, v[2:3]
	v_lshl_add_u64 v[12:13], v[12:13], 2, s[46:47]
	global_load_dword v199, v[12:13], off offset:248
.LBB0_135:
.LBB0_136:
	s_ashr_i32 s53, s52, 31
	v_mov_b32_e32 v12, v15
	s_waitcnt vmcnt(0)
	s_and_b64 vcc, exec, s[40:41]
	s_cbranch_vccz .Ltp0_nomul_2
	v_mul_f32_e32 v152, v152, v184
	v_mul_f32_e32 v153, v153, v185
	v_mul_f32_e32 v154, v154, v186
	v_mul_f32_e32 v155, v155, v187
	v_mul_f32_e32 v156, v156, v188
	v_mul_f32_e32 v157, v157, v189
	v_mul_f32_e32 v158, v158, v190
	v_mul_f32_e32 v159, v159, v191
	v_mul_f32_e32 v160, v160, v192
	v_mul_f32_e32 v161, v161, v193
	v_mul_f32_e32 v162, v162, v194
	v_mul_f32_e32 v163, v163, v195
	v_mul_f32_e32 v164, v164, v196
	v_mul_f32_e32 v165, v165, v197
	v_mul_f32_e32 v166, v166, v198
	v_mul_f32_e32 v167, v167, v199
.Ltp0_nomul_2:
	v_add_u32_e32 v15, v51, v56
	ds_write_b32 v15, v152
	v_add_u32_e32 v15, v51, v60
	ds_write_b32 v15, v153
	v_add_u32_e32 v15, v51, v61
	ds_write_b32 v15, v154
	v_add_u32_e32 v15, v51, v62
	ds_write_b32 v15, v155
	v_add_u32_e32 v15, v51, v52
	ds_write_b32 v15, v156
	v_add_u32_e32 v15, v51, v63
	ds_write_b32 v15, v157
	v_add_u32_e32 v15, v51, v64
	ds_write_b32 v15, v158
	v_add_u32_e32 v15, v51, v65
	ds_write_b32 v15, v159
	v_add_u32_e32 v15, v51, v53
	ds_write_b32 v15, v160
	v_add_u32_e32 v15, v51, v67
	ds_write_b32 v15, v161
	v_add_u32_e32 v14, v51, v54
	ds_write_b32 v14, v162
	ds_write_b32 v14, v163 offset:264
	ds_write_b32 v14, v164 offset:528
	ds_write_b32 v14, v165 offset:792
	ds_write_b32 v14, v166 offset:1056
	v_mov_b32_e32 v12, v167
	s_branch .LBB0_6

; __device__ __forceinline__ void transpose_mat(const float* __restrict__ W, int K, int N, int Npad, bf16_t* __restrict__ WT, int blk_mul, int blk_off,
;                                               LAS float* scr, int gw, int NGW, int lane, const float* __restrict__ gk = nullptr) {
;     ...
;         const int kb = it / nblk, nb = it % nblk, k0 = 64 * kb, n0 = 32 * nb;
;         const int ncol = n0 + (lane & 31);
; #pragma unroll
;         for (int i = 0; i < 32; ++i) { const int kk = 2 * i + (lane >> 5); float w = (ncol < N) ? W[(size_t)(k0 + kk) * N + ncol] : 0.f; if (gk) w *= gk[k0 + kk]; scr[kk * 33 + (lane & 31)] = w; }
; __device__ __forceinline__ void convert_layer(int l, const float* w_gate, const float* w_up, const float* w_down, const float* ffn_g, const float* w_in, const float* mix_g, ...
;     ...
;         transpose_mat(w_gate + wo, DM, FF, FF, (bf16_t*)(ws + WS_WGU + lf * SZ_WGU), 256, 0, scr, gw, NGW, lane, ffn_g + (size_t)lf * DM);
;         transpose_mat(w_up + wo, DM, FF, FF, (bf16_t*)(ws + WS_WGU + lf * SZ_WGU), 256, 128, scr, gw, NGW, lane, ffn_g + (size_t)lf * DM);
.LBB0_142:
	s_mul_hi_i32 s2, s34, 0x2e8ba2e9
	s_lshr_b32 s3, s2, 31
	s_ashr_i32 s45, s2, 4
	s_add_i32 s45, s45, s3
	s_mul_i32 s67, s45, 0xfffff500
	s_add_i32 s2, s67, s65
	v_add_u32_e32 v12, s2, v81
	s_lshl_b32 s48, s45, 6
	v_ashrrev_i32_e32 v13, 31, v12
	v_cmp_gt_i32_e64 s[2:3], s59, v12
	v_lshl_add_u64 v[12:13], v[12:13], 2, s[52:53]
	v_mov_b32_e32 v136, 0
	v_or_b32_e32 v14, s48, v2
	s_and_saveexec_b64 s[4:5], s[2:3]
	s_cbranch_execz .LBB0_144
	v_mad_i64_i32 v[84:85], s[54:55], v14, s60, v[12:13]
	global_load_dword v136, v[84:85], off
.LBB0_144:
	s_or_b64 exec, exec, s[4:5]
	v_cndmask_b32_e64 v6, 0, 1, s[40:41]
	v_cmp_ne_u32_e64 s[4:5], 1, v6
	s_andn2_b64 vcc, exec, s[40:41]
	s_cbranch_vccnz .LBB0_146
	v_ashrrev_i32_e32 v15, 31, v14
	v_lshl_add_u64 v[14:15], v[14:15], 2, s[46:47]
	global_load_dword v168, v[14:15], off
.LBB0_146:
	v_mov_b32_e32 v137, 0
	s_and_saveexec_b64 s[54:55], s[2:3]
	s_cbranch_execz .LBB0_148
	v_or_b32_e32 v14, s48, v19
	v_mad_i64_i32 v[14:15], s[68:69], v14, s60, v[12:13]
	global_load_dword v137, v[14:15], off
.LBB0_148:
	s_or_b64 exec, exec, s[54:55]
	s_and_b64 vcc, exec, s[4:5]
	s_cbranch_vccnz .LBB0_150
	s_ashr_i32 s49, s48, 31
	v_lshl_add_u64 v[84:85], s[48:49], 0, v[2:3]
	v_lshl_add_u64 v[84:85], v[84:85], 2, s[46:47]
	global_load_dword v169, v[84:85], off offset:8
.LBB0_150:
	v_mov_b32_e32 v138, 0
	s_and_saveexec_b64 s[54:55], s[2:3]
	s_cbranch_execz .LBB0_152
	v_or_b32_e32 v14, s48, v20
	v_mad_i64_i32 v[14:15], s[68:69], v14, s60, v[12:13]
	global_load_dword v138, v[14:15], off
.LBB0_152:
	s_or_b64 exec, exec, s[54:55]
	s_and_b64 vcc, exec, s[4:5]
	s_cbranch_vccnz .LBB0_154
	s_ashr_i32 s49, s48, 31
	v_lshl_add_u64 v[84:85], s[48:49], 0, v[2:3]
	v_lshl_add_u64 v[84:85], v[84:85], 2, s[46:47]
	global_load_dword v170, v[84:85], off offset:16
.LBB0_154:
	v_mov_b32_e32 v139, 0
	s_and_saveexec_b64 s[54:55], s[2:3]
	s_cbranch_execz .LBB0_156
	v_or_b32_e32 v14, s48, v21
	v_mad_i64_i32 v[14:15], s[68:69], v14, s60, v[12:13]
	global_load_dword v139, v[14:15], off
.LBB0_156:
	s_or_b64 exec, exec, s[54:55]
	s_and_b64 vcc, exec, s[4:5]
	s_cbranch_vccnz .LBB0_158
	s_ashr_i32 s49, s48, 31
	v_lshl_add_u64 v[84:85], s[48:49], 0, v[2:3]
	v_lshl_add_u64 v[84:85], v[84:85], 2, s[46:47]
	global_load_dword v171, v[84:85], off offset:24
.LBB0_158:
	v_mov_b32_e32 v140, 0
	s_and_saveexec_b64 s[54:55], s[2:3]
	s_cbranch_execz .LBB0_160
	v_or_b32_e32 v14, s48, v22
	v_mad_i64_i32 v[14:15], s[68:69], v14, s60, v[12:13]
	global_load_dword v140, v[14:15], off
.LBB0_160:
	s_or_b64 exec, exec, s[54:55]
	s_and_b64 vcc, exec, s[4:5]
	s_cbranch_vccnz .LBB0_162
	s_ashr_i32 s49, s48, 31
	v_lshl_add_u64 v[84:85], s[48:49], 0, v[2:3]
	v_lshl_add_u64 v[84:85], v[84:85], 2, s[46:47]
	global_load_dword v172, v[84:85], off offset:32
.LBB0_162:
	v_mov_b32_e32 v141, 0
	s_and_saveexec_b64 s[54:55], s[2:3]
	s_cbranch_execz .LBB0_164
	v_or_b32_e32 v15, s48, v23
	v_mad_i64_i32 v[84:85], s[68:69], v15, s60, v[12:13]
	global_load_dword v141, v[84:85], off
.LBB0_164:
	s_or_b64 exec, exec, s[54:55]
	s_and_b64 vcc, exec, s[4:5]
	s_cbranch_vccnz .LBB0_166
	s_ashr_i32 s49, s48, 31
	v_lshl_add_u64 v[84:85], s[48:49], 0, v[2:3]
	v_lshl_add_u64 v[84:85], v[84:85], 2, s[46:47]
	global_load_dword v173, v[84:85], off offset:40
.LBB0_166:
	v_mov_b32_e32 v142, 0
	s_and_saveexec_b64 s[54:55], s[2:3]
	s_cbranch_execz .LBB0_168
	v_or_b32_e32 v15, s48, v24
	v_mad_i64_i32 v[84:85], s[68:69], v15, s60, v[12:13]
	global_load_dword v142, v[84:85], off
.LBB0_168:
	s_or_b64 exec, exec, s[54:55]
	s_and_b64 vcc, exec, s[4:5]
	s_cbranch_vccnz .LBB0_170
	s_ashr_i32 s49, s48, 31
	v_lshl_add_u64 v[84:85], s[48:49], 0, v[2:3]
	v_lshl_add_u64 v[84:85], v[84:85], 2, s[46:47]
	global_load_dword v174, v[84:85], off offset:48
.LBB0_170:
	v_mov_b32_e32 v143, 0
	s_and_saveexec_b64 s[54:55], s[2:3]
	s_cbranch_execz .LBB0_172
	v_or_b32_e32 v15, s48, v25
	v_mad_i64_i32 v[84:85], s[68:69], v15, s60, v[12:13]
	global_load_dword v143, v[84:85], off
; __device__ __forceinline__ void transpose_mat(const float* __restrict__ W, int K, int N, int Npad, bf16_t* __restrict__ WT, int blk_mul, int blk_off,
;                                               LAS float* scr, int gw, int NGW, int lane, const float* __restrict__ gk = nullptr) {
;     ...
;         const int kb = it / nblk, nb = it % nblk, k0 = 64 * kb, n0 = 32 * nb;
;         const int ncol = n0 + (lane & 31);
; #pragma unroll
;         for (int i = 0; i < 32; ++i) { const int kk = 2 * i + (lane >> 5); float w = (ncol < N) ? W[(size_t)(k0 + kk) * N + ncol] : 0.f; if (gk) w *= gk[k0 + kk]; scr[kk * 33 + (lane & 31)] = w; }
.LBB0_172:
	s_or_b64 exec, exec, s[54:55]
	s_and_b64 vcc, exec, s[4:5]
	s_cbranch_vccnz .LBB0_174
	s_ashr_i32 s49, s48, 31
	v_lshl_add_u64 v[84:85], s[48:49], 0, v[2:3]
	v_lshl_add_u64 v[84:85], v[84:85], 2, s[46:47]
	global_load_dword v175, v[84:85], off offset:56
.LBB0_174:
	v_mov_b32_e32 v144, 0
	s_and_saveexec_b64 s[54:55], s[2:3]
	s_cbranch_execz .LBB0_176
	v_or_b32_e32 v15, s48, v27
	v_mad_i64_i32 v[84:85], s[68:69], v15, s60, v[12:13]
	global_load_dword v144, v[84:85], off
.LBB0_176:
	s_or_b64 exec, exec, s[54:55]
	s_and_b64 vcc, exec, s[4:5]
	s_cbranch_vccnz .LBB0_178
	s_ashr_i32 s49, s48, 31
	v_lshl_add_u64 v[84:85], s[48:49], 0, v[2:3]
	v_lshl_add_u64 v[84:85], v[84:85], 2, s[46:47]
	global_load_dword v176, v[84:85], off offset:64
.LBB0_178:
	v_mov_b32_e32 v145, 0
	s_and_saveexec_b64 s[54:55], s[2:3]
	s_cbranch_execz .LBB0_180
	v_or_b32_e32 v80, s48, v28
	v_mad_i64_i32 v[84:85], s[68:69], v80, s60, v[12:13]
	global_load_dword v145, v[84:85], off
.LBB0_180:
	s_or_b64 exec, exec, s[54:55]
	s_and_b64 vcc, exec, s[4:5]
	s_cbranch_vccnz .LBB0_182
	s_ashr_i32 s49, s48, 31
	v_lshl_add_u64 v[84:85], s[48:49], 0, v[2:3]
	v_lshl_add_u64 v[84:85], v[84:85], 2, s[46:47]
	global_load_dword v177, v[84:85], off offset:72
.LBB0_182:
	v_mov_b32_e32 v146, 0
	s_and_saveexec_b64 s[54:55], s[2:3]
	s_cbranch_execz .LBB0_184
	v_or_b32_e32 v80, s48, v29
	v_mad_i64_i32 v[84:85], s[68:69], v80, s60, v[12:13]
	global_load_dword v146, v[84:85], off
.LBB0_184:
	s_or_b64 exec, exec, s[54:55]
	s_and_b64 vcc, exec, s[4:5]
	s_cbranch_vccnz .LBB0_186
	s_ashr_i32 s49, s48, 31
	v_lshl_add_u64 v[84:85], s[48:49], 0, v[2:3]
	v_lshl_add_u64 v[84:85], v[84:85], 2, s[46:47]
	global_load_dword v178, v[84:85], off offset:80
.LBB0_186:
	v_mov_b32_e32 v147, 0
	s_and_saveexec_b64 s[54:55], s[2:3]
	s_cbranch_execz .LBB0_188
	v_or_b32_e32 v80, s48, v30
	v_mad_i64_i32 v[84:85], s[68:69], v80, s60, v[12:13]
	global_load_dword v147, v[84:85], off
.LBB0_188:
	s_or_b64 exec, exec, s[54:55]
	s_and_b64 vcc, exec, s[4:5]
	s_cbranch_vccnz .LBB0_190
	s_ashr_i32 s49, s48, 31
	v_lshl_add_u64 v[84:85], s[48:49], 0, v[2:3]
	v_lshl_add_u64 v[84:85], v[84:85], 2, s[46:47]
	global_load_dword v179, v[84:85], off offset:88
.LBB0_190:
	v_mov_b32_e32 v148, 0
	s_and_saveexec_b64 s[54:55], s[2:3]
	s_cbranch_execz .LBB0_192
	v_or_b32_e32 v80, s48, v31
	v_mad_i64_i32 v[84:85], s[68:69], v80, s60, v[12:13]
	global_load_dword v148, v[84:85], off
.LBB0_192:
	s_or_b64 exec, exec, s[54:55]
	s_and_b64 vcc, exec, s[4:5]
	s_cbranch_vccnz .LBB0_194
	s_ashr_i32 s49, s48, 31
	v_lshl_add_u64 v[84:85], s[48:49], 0, v[2:3]
	v_lshl_add_u64 v[84:85], v[84:85], 2, s[46:47]
	global_load_dword v180, v[84:85], off offset:96
.LBB0_194:
	v_mov_b32_e32 v149, 0
	s_and_saveexec_b64 s[54:55], s[2:3]
	s_cbranch_execz .LBB0_196
	v_or_b32_e32 v83, s48, v32
	v_mad_i64_i32 v[84:85], s[68:69], v83, s60, v[12:13]
	global_load_dword v149, v[84:85], off
.LBB0_196:
	s_or_b64 exec, exec, s[54:55]
	s_and_b64 vcc, exec, s[4:5]
	s_cbranch_vccnz .LBB0_198
	s_ashr_i32 s49, s48, 31
	v_lshl_add_u64 v[84:85], s[48:49], 0, v[2:3]
	v_lshl_add_u64 v[84:85], v[84:85], 2, s[46:47]
	global_load_dword v181, v[84:85], off offset:104
.LBB0_198:
	v_mov_b32_e32 v150, 0
	s_and_saveexec_b64 s[54:55], s[2:3]
	s_cbranch_execz .LBB0_200
	v_or_b32_e32 v83, s48, v33
	v_mad_i64_i32 v[84:85], s[68:69], v83, s60, v[12:13]
	global_load_dword v150, v[84:85], off
.LBB0_200:
	s_or_b64 exec, exec, s[54:55]
	s_and_b64 vcc, exec, s[4:5]
	s_cbranch_vccnz .LBB0_202
	s_ashr_i32 s49, s48, 31
	v_lshl_add_u64 v[84:85], s[48:49], 0, v[2:3]
	v_lshl_add_u64 v[84:85], v[84:85], 2, s[46:47]
	global_load_dword v182, v[84:85], off offset:112
.LBB0_202:
	v_mov_b32_e32 v151, 0
	s_and_saveexec_b64 s[54:55], s[2:3]
	s_cbranch_execz .LBB0_204
	v_or_b32_e32 v83, s48, v34
	v_mad_i64_i32 v[84:85], s[68:69], v83, s60, v[12:13]
	global_load_dword v151, v[84:85], off
.LBB0_204:
	s_or_b64 exec, exec, s[54:55]
	s_and_b64 vcc, exec, s[4:5]
	s_cbranch_vccnz .LBB0_206
	s_ashr_i32 s49, s48, 31
	v_lshl_add_u64 v[84:85], s[48:49], 0, v[2:3]
	v_lshl_add_u64 v[84:85], v[84:85], 2, s[46:47]
	global_load_dword v183, v[84:85], off offset:120

; #define LDS_WAIT() asm volatile("s_waitcnt lgkmcnt(0)" ::: "memory")
; __device__ __forceinline__ void transpose_mat(const float* __restrict__ W, int K, int N, int Npad, bf16_t* __restrict__ WT, int blk_mul, int blk_off,
;                                               LAS float* scr, int gw, int NGW, int lane, const float* __restrict__ gk = nullptr) {
;     ...
;         const int kb = it / nblk, nb = it % nblk, k0 = 64 * kb, n0 = 32 * nb;
;         const int ncol = n0 + (lane & 31);
; #pragma unroll
;         for (int i = 0; i < 32; ++i) { const int kk = 2 * i + (lane >> 5); float w = (ncol < N) ? W[(size_t)(k0 + kk) * N + ncol] : 0.f; if (gk) w *= gk[k0 + kk]; scr[kk * 33 + (lane & 31)] = w; }
;         LDS_WAIT();
.Ltp1_nomul_1:
	v_add_u32_e32 v6, v51, v5
	ds_write_b32 v6, v136
	v_add_u32_e32 v15, v51, v69
	ds_write_b32 v15, v137
	v_add_u32_e32 v15, v51, v70
	ds_write_b32 v15, v138
	v_add_u32_e32 v15, v51, v71
	ds_write_b32 v15, v139
	v_add_u32_e32 v14, v51, v68
	ds_write_b32 v14, v140
	v_add_u32_e32 v80, v51, v72
	ds_write_b32 v80, v141
	v_add_u32_e32 v80, v51, v73
	ds_write_b32 v80, v142
	v_add_u32_e32 v80, v51, v74
	ds_write_b32 v80, v143
	v_add_u32_e32 v15, v51, v78
	ds_write_b32 v15, v144
	v_add_u32_e32 v83, v51, v75
	ds_write_b32 v83, v145
	v_add_u32_e32 v83, v51, v76
	ds_write_b32 v83, v146
	v_add_u32_e32 v83, v51, v77
	ds_write_b32 v83, v147
	v_add_u32_e32 v80, v51, v55
	ds_write_b32 v80, v148
	v_add_u32_e32 v84, v51, v57
	ds_write_b32 v84, v149
	v_add_u32_e32 v84, v51, v58
	ds_write_b32 v84, v150
	v_add_u32_e32 v84, v51, v59
	ds_write_b32 v84, v151
	v_mov_b32_e32 v152, 0
	s_and_saveexec_b64 s[54:55], s[2:3]
	s_cbranch_execz .LBB0_208
	v_or_b32_e32 v83, s48, v35
	v_mad_i64_i32 v[84:85], s[68:69], v83, s60, v[12:13]
	global_load_dword v152, v[84:85], off
.LBB0_208:
	s_or_b64 exec, exec, s[54:55]
	s_and_b64 vcc, exec, s[4:5]
	s_cbranch_vccnz .LBB0_210
	s_ashr_i32 s49, s48, 31
	v_lshl_add_u64 v[86:87], s[48:49], 0, v[2:3]
	v_lshl_add_u64 v[86:87], v[86:87], 2, s[46:47]
	global_load_dword v184, v[86:87], off offset:128
.LBB0_210:
	v_mov_b32_e32 v153, 0
	s_and_saveexec_b64 s[54:55], s[2:3]
	s_cbranch_execz .LBB0_212
	v_or_b32_e32 v84, s48, v36
	v_mad_i64_i32 v[84:85], s[68:69], v84, s60, v[12:13]
	global_load_dword v153, v[84:85], off
.LBB0_212:
	s_or_b64 exec, exec, s[54:55]
	s_and_b64 vcc, exec, s[4:5]
	s_cbranch_vccnz .LBB0_214
	s_ashr_i32 s49, s48, 31
	v_lshl_add_u64 v[86:87], s[48:49], 0, v[2:3]
	v_lshl_add_u64 v[86:87], v[86:87], 2, s[46:47]
	global_load_dword v185, v[86:87], off offset:136
.LBB0_214:
	v_mov_b32_e32 v154, 0
	s_and_saveexec_b64 s[54:55], s[2:3]
	s_cbranch_execz .LBB0_216
	v_or_b32_e32 v84, s48, v37
	v_mad_i64_i32 v[84:85], s[68:69], v84, s60, v[12:13]
	global_load_dword v154, v[84:85], off
.LBB0_216:
	s_or_b64 exec, exec, s[54:55]
	s_and_b64 vcc, exec, s[4:5]
	s_cbranch_vccnz .LBB0_218
	s_ashr_i32 s49, s48, 31
	v_lshl_add_u64 v[86:87], s[48:49], 0, v[2:3]
	v_lshl_add_u64 v[86:87], v[86:87], 2, s[46:47]
	global_load_dword v186, v[86:87], off offset:144
.LBB0_218:
	v_mov_b32_e32 v155, 0
	s_and_saveexec_b64 s[54:55], s[2:3]
	s_cbranch_execz .LBB0_220
	v_or_b32_e32 v84, s48, v38
	v_mad_i64_i32 v[84:85], s[68:69], v84, s60, v[12:13]
	global_load_dword v155, v[84:85], off
.LBB0_220:
	s_or_b64 exec, exec, s[54:55]
	s_and_b64 vcc, exec, s[4:5]
	s_cbranch_vccnz .LBB0_222
	s_ashr_i32 s49, s48, 31
	v_lshl_add_u64 v[86:87], s[48:49], 0, v[2:3]
	v_lshl_add_u64 v[86:87], v[86:87], 2, s[46:47]
	global_load_dword v187, v[86:87], off offset:152
.LBB0_222:
	v_mov_b32_e32 v156, 0
	s_and_saveexec_b64 s[54:55], s[2:3]
	s_cbranch_execz .LBB0_224
	v_or_b32_e32 v84, s48, v39
	v_mad_i64_i32 v[84:85], s[68:69], v84, s60, v[12:13]
	global_load_dword v156, v[84:85], off
.LBB0_224:
	s_or_b64 exec, exec, s[54:55]
	s_and_b64 vcc, exec, s[4:5]
	s_cbranch_vccnz .LBB0_226
	s_ashr_i32 s49, s48, 31
	v_lshl_add_u64 v[86:87], s[48:49], 0, v[2:3]
	v_lshl_add_u64 v[86:87], v[86:87], 2, s[46:47]
	global_load_dword v188, v[86:87], off offset:160
.LBB0_226:
	v_mov_b32_e32 v157, 0
	s_and_saveexec_b64 s[54:55], s[2:3]
	s_cbranch_execz .LBB0_228
	v_or_b32_e32 v85, s48, v40
	v_mad_i64_i32 v[86:87], s[68:69], v85, s60, v[12:13]
	global_load_dword v157, v[86:87], off
.LBB0_228:
	s_or_b64 exec, exec, s[54:55]
	s_and_b64 vcc, exec, s[4:5]
	s_cbranch_vccnz .LBB0_230
	s_ashr_i32 s49, s48, 31
	v_lshl_add_u64 v[86:87], s[48:49], 0, v[2:3]
	v_lshl_add_u64 v[86:87], v[86:87], 2, s[46:47]
	global_load_dword v189, v[86:87], off offset:168
.LBB0_230:
	v_mov_b32_e32 v158, 0
	s_and_saveexec_b64 s[54:55], s[2:3]
	s_cbranch_execz .LBB0_232
	v_or_b32_e32 v85, s48, v41
	v_mad_i64_i32 v[86:87], s[68:69], v85, s60, v[12:13]
	global_load_dword v158, v[86:87], off
.LBB0_232:
	s_or_b64 exec, exec, s[54:55]
	s_and_b64 vcc, exec, s[4:5]
	s_cbranch_vccnz .LBB0_234
	s_ashr_i32 s49, s48, 31
	v_lshl_add_u64 v[86:87], s[48:49], 0, v[2:3]
	v_lshl_add_u64 v[86:87], v[86:87], 2, s[46:47]
	global_load_dword v190, v[86:87], off offset:176
.LBB0_234:
	v_mov_b32_e32 v159, 0
	s_and_saveexec_b64 s[54:55], s[2:3]
	s_cbranch_execz .LBB0_236
	v_or_b32_e32 v85, s48, v42
	v_mad_i64_i32 v[86:87], s[68:69], v85, s60, v[12:13]
	global_load_dword v159, v[86:87], off
.LBB0_236:
	s_or_b64 exec, exec, s[54:55]
	s_and_b64 vcc, exec, s[4:5]
	s_cbranch_vccnz .LBB0_238
	s_ashr_i32 s49, s48, 31
	v_lshl_add_u64 v[86:87], s[48:49], 0, v[2:3]
	v_lshl_add_u64 v[86:87], v[86:87], 2, s[46:47]
	global_load_dword v191, v[86:87], off offset:184
.LBB0_238:
	v_mov_b32_e32 v160, 0
	s_and_saveexec_b64 s[54:55], s[2:3]
	s_cbranch_execz .LBB0_240
	v_or_b32_e32 v85, s48, v43
	v_mad_i64_i32 v[86:87], s[68:69], v85, s60, v[12:13]
	global_load_dword v160, v[86:87], off
; #define LDS_WAIT() asm volatile("s_waitcnt lgkmcnt(0)" ::: "memory")
; __device__ __forceinline__ void transpose_mat(const float* __restrict__ W, int K, int N, int Npad, bf16_t* __restrict__ WT, int blk_mul, int blk_off,
;                                               LAS float* scr, int gw, int NGW, int lane, const float* __restrict__ gk = nullptr) {
;     ...
;         const int kb = it / nblk, nb = it % nblk, k0 = 64 * kb, n0 = 32 * nb;
;         const int ncol = n0 + (lane & 31);
; #pragma unroll
;         for (int i = 0; i < 32; ++i) { const int kk = 2 * i + (lane >> 5); float w = (ncol < N) ? W[(size_t)(k0 + kk) * N + ncol] : 0.f; if (gk) w *= gk[k0 + kk]; scr[kk * 33 + (lane & 31)] = w; }
;         LDS_WAIT();
.LBB0_240:
	s_or_b64 exec, exec, s[54:55]
	s_and_b64 vcc, exec, s[4:5]
	s_cbranch_vccnz .LBB0_242
	s_ashr_i32 s49, s48, 31
	v_lshl_add_u64 v[88:89], s[48:49], 0, v[2:3]
	v_lshl_add_u64 v[88:89], v[88:89], 2, s[46:47]
	global_load_dword v192, v[88:89], off offset:192
.LBB0_242:
	v_mov_b32_e32 v161, 0
	s_and_saveexec_b64 s[54:55], s[2:3]
	s_cbranch_execz .LBB0_244
	v_or_b32_e32 v86, s48, v44
	v_mad_i64_i32 v[86:87], s[68:69], v86, s60, v[12:13]
	global_load_dword v161, v[86:87], off
.LBB0_244:
	s_or_b64 exec, exec, s[54:55]
	s_and_b64 vcc, exec, s[4:5]
	s_cbranch_vccnz .LBB0_246
	s_ashr_i32 s49, s48, 31
	v_lshl_add_u64 v[88:89], s[48:49], 0, v[2:3]
	v_lshl_add_u64 v[88:89], v[88:89], 2, s[46:47]
	global_load_dword v193, v[88:89], off offset:200
.LBB0_246:
	v_mov_b32_e32 v162, 0
	s_and_saveexec_b64 s[54:55], s[2:3]
	s_cbranch_execz .LBB0_248
	v_or_b32_e32 v86, s48, v45
	v_mad_i64_i32 v[86:87], s[68:69], v86, s60, v[12:13]
	global_load_dword v162, v[86:87], off
.LBB0_248:
	s_or_b64 exec, exec, s[54:55]
	s_and_b64 vcc, exec, s[4:5]
	s_cbranch_vccnz .LBB0_250
	s_ashr_i32 s49, s48, 31
	v_lshl_add_u64 v[88:89], s[48:49], 0, v[2:3]
	v_lshl_add_u64 v[88:89], v[88:89], 2, s[46:47]
	global_load_dword v194, v[88:89], off offset:208
.LBB0_250:
	v_mov_b32_e32 v163, 0
	s_and_saveexec_b64 s[54:55], s[2:3]
	s_cbranch_execz .LBB0_252
	v_or_b32_e32 v87, s48, v46
	v_mad_i64_i32 v[88:89], s[68:69], v87, s60, v[12:13]
	global_load_dword v163, v[88:89], off
.LBB0_252:
	s_or_b64 exec, exec, s[54:55]
	s_and_b64 vcc, exec, s[4:5]
	s_cbranch_vccnz .LBB0_254
	s_ashr_i32 s49, s48, 31
	v_lshl_add_u64 v[88:89], s[48:49], 0, v[2:3]
	v_lshl_add_u64 v[88:89], v[88:89], 2, s[46:47]
	global_load_dword v195, v[88:89], off offset:216
.LBB0_254:
	v_mov_b32_e32 v164, 0
	s_and_saveexec_b64 s[54:55], s[2:3]
	s_cbranch_execz .LBB0_256
	v_or_b32_e32 v87, s48, v47
	v_mad_i64_i32 v[88:89], s[68:69], v87, s60, v[12:13]
	global_load_dword v164, v[88:89], off
.LBB0_256:
	s_or_b64 exec, exec, s[54:55]
	s_and_b64 vcc, exec, s[4:5]
	s_cbranch_vccnz .LBB0_258
	s_ashr_i32 s49, s48, 31
	v_lshl_add_u64 v[88:89], s[48:49], 0, v[2:3]
	v_lshl_add_u64 v[88:89], v[88:89], 2, s[46:47]
	global_load_dword v196, v[88:89], off offset:224
.LBB0_258:
	v_mov_b32_e32 v165, 0
	s_and_saveexec_b64 s[54:55], s[2:3]
	s_cbranch_execz .LBB0_260
	v_or_b32_e32 v87, s48, v48
	v_mad_i64_i32 v[88:89], s[68:69], v87, s60, v[12:13]
	global_load_dword v165, v[88:89], off
.LBB0_260:
	s_or_b64 exec, exec, s[54:55]
	s_and_b64 vcc, exec, s[4:5]
	s_cbranch_vccnz .LBB0_262
	s_ashr_i32 s49, s48, 31
	v_lshl_add_u64 v[88:89], s[48:49], 0, v[2:3]
	v_lshl_add_u64 v[88:89], v[88:89], 2, s[46:47]
	global_load_dword v197, v[88:89], off offset:232
.LBB0_262:
	v_mov_b32_e32 v166, 0
	s_and_saveexec_b64 s[54:55], s[2:3]
	s_cbranch_execz .LBB0_264
	v_or_b32_e32 v87, s48, v49
	v_mad_i64_i32 v[88:89], s[68:69], v87, s60, v[12:13]
	global_load_dword v166, v[88:89], off
.LBB0_264:
	s_or_b64 exec, exec, s[54:55]
	s_and_b64 vcc, exec, s[4:5]
	s_cbranch_vccnz .LBB0_266
	s_ashr_i32 s49, s48, 31
	v_lshl_add_u64 v[88:89], s[48:49], 0, v[2:3]
	v_lshl_add_u64 v[88:89], v[88:89], 2, s[46:47]
	global_load_dword v198, v[88:89], off offset:240
.LBB0_266:
	v_mov_b32_e32 v167, 0
	s_and_saveexec_b64 s[4:5], s[2:3]
	s_cbranch_execz .LBB0_268
	v_or_b32_e32 v87, s48, v50
	v_mad_i64_i32 v[12:13], s[2:3], v87, s60, v[12:13]
	global_load_dword v167, v[12:13], off
.LBB0_268:
	s_or_b64 exec, exec, s[4:5]
	s_and_b64 vcc, exec, s[40:41]
	s_cbranch_vccz .LBB0_270
	s_ashr_i32 s49, s48, 31
	v_lshl_add_u64 v[12:13], s[48:49], 0, v[2:3]
	v_lshl_add_u64 v[12:13], v[12:13], 2, s[46:47]
	global_load_dword v199, v[12:13], off offset:248
.LBB0_270:
.LBB0_271:
	s_ashr_i32 s49, s48, 31
	v_mov_b32_e32 v12, v87
	s_waitcnt vmcnt(0)
	s_and_b64 vcc, exec, s[40:41]
	s_cbranch_vccz .Ltp1_nomul_2
	v_mul_f32_e32 v152, v152, v184
	v_mul_f32_e32 v153, v153, v185
	v_mul_f32_e32 v154, v154, v186
	v_mul_f32_e32 v155, v155, v187
	v_mul_f32_e32 v156, v156, v188
	v_mul_f32_e32 v157, v157, v189
	v_mul_f32_e32 v158, v158, v190
	v_mul_f32_e32 v159, v159, v191
	v_mul_f32_e32 v160, v160, v192
	v_mul_f32_e32 v161, v161, v193
	v_mul_f32_e32 v162, v162, v194
	v_mul_f32_e32 v163, v163, v195
	v_mul_f32_e32 v164, v164, v196
	v_mul_f32_e32 v165, v165, v197
	v_mul_f32_e32 v166, v166, v198
	v_mul_f32_e32 v167, v167, v199
.Ltp1_nomul_2:
	v_add_u32_e32 v83, v51, v56
	ds_write_b32 v83, v152
	v_add_u32_e32 v85, v51, v60
	ds_write_b32 v85, v153
	v_add_u32_e32 v85, v51, v61
	ds_write_b32 v85, v154
	v_add_u32_e32 v85, v51, v62
	ds_write_b32 v85, v155
	v_add_u32_e32 v84, v51, v52
	ds_write_b32 v84, v156
	v_add_u32_e32 v86, v51, v63
	ds_write_b32 v86, v157
	v_add_u32_e32 v86, v51, v64
	ds_write_b32 v86, v158
	v_add_u32_e32 v86, v51, v65
	ds_write_b32 v86, v159
	v_add_u32_e32 v85, v51, v53
	ds_write_b32 v85, v160
	v_add_u32_e32 v87, v51, v67
	ds_write_b32 v87, v161
	v_add_u32_e32 v86, v51, v54
	ds_write_b32 v86, v162
	ds_write_b32 v86, v163 offset:264
	ds_write_b32 v86, v164 offset:528
	ds_write_b32 v86, v165 offset:792
	ds_write_b32 v86, v166 offset:1056
	v_mov_b32_e32 v12, v167
	s_branch .LBB0_141

; __device__ __forceinline__ void transpose_mat(const float* __restrict__ W, int K, int N, int Npad, bf16_t* __restrict__ WT, int blk_mul, int blk_off,
;                                               LAS float* scr, int gw, int NGW, int lane, const float* __restrict__ gk = nullptr) {
;     ...
;         const int kb = it / nblk, nb = it % nblk, k0 = 64 * kb, n0 = 32 * nb;
;         const int ncol = n0 + (lane & 31);
; #pragma unroll
;         for (int i = 0; i < 32; ++i) { const int kk = 2 * i + (lane >> 5); float w = (ncol < N) ? W[(size_t)(k0 + kk) * N + ncol] : 0.f; if (gk) w *= gk[k0 + kk]; scr[kk * 33 + (lane & 31)] = w; }
; __device__ __forceinline__ void convert_layer(int l, const float* w_gate, const float* w_up, const float* w_down, const float* ffn_g, const float* w_in, const float* mix_g, ...
;     ...
;     transpose_mat(w_in + (size_t)l * DM * NIN, DM, NIN, NPJ, (bf16_t*)(ws + WS_WIN + l * SZ_WIN), 128, 0, scr, gw, NGW, lane, mix_g + (size_t)l * DM);
.LBB0_293:
	s_mul_hi_i32 s4, s34, 0x66666667
	s_lshr_b32 s5, s4, 31
	s_ashr_i32 s4, s4, 5
	s_add_i32 s4, s4, s5
	s_mul_i32 s35, s4, 0xfffff600
	s_add_i32 s35, s35, s7
	v_add_u32_e32 v8, s35, v26
	s_lshl_b32 s10, s4, 6
	v_ashrrev_i32_e32 v9, 31, v8
	v_cmp_gt_i32_e64 s[4:5], s15, v8
	v_lshl_add_u64 v[8:9], v[8:9], 2, s[18:19]
	v_or_b32_e32 v10, s10, v2
	v_mov_b32_e32 v136, 0
	s_and_saveexec_b64 s[12:13], s[4:5]
	s_cbranch_execz .LBB0_295
	v_mad_i64_i32 v[76:77], s[36:37], v10, s33, v[8:9]
	global_load_dword v136, v[76:77], off
.LBB0_295:
	s_or_b64 exec, exec, s[12:13]
	s_and_b64 vcc, exec, s[2:3]
	s_cbranch_vccnz .LBB0_297
	v_ashrrev_i32_e32 v11, 31, v10
	v_lshl_add_u64 v[10:11], v[10:11], 2, s[16:17]
	global_load_dword v168, v[10:11], off
.LBB0_297:
	v_mov_b32_e32 v137, 0
	s_and_saveexec_b64 s[12:13], s[4:5]
	s_cbranch_execz .LBB0_299
	v_or_b32_e32 v10, s10, v19
	v_mad_i64_i32 v[10:11], s[36:37], v10, s33, v[8:9]
	global_load_dword v137, v[10:11], off
.LBB0_299:
	s_or_b64 exec, exec, s[12:13]
	s_and_b64 vcc, exec, s[2:3]
	s_cbranch_vccnz .LBB0_301
	s_ashr_i32 s11, s10, 31
	v_lshl_add_u64 v[76:77], s[10:11], 0, v[2:3]
	v_lshl_add_u64 v[76:77], v[76:77], 2, s[16:17]
	global_load_dword v169, v[76:77], off offset:8
.LBB0_301:
	v_mov_b32_e32 v138, 0
	s_and_saveexec_b64 s[12:13], s[4:5]
	s_cbranch_execz .LBB0_303
	v_or_b32_e32 v10, s10, v20
	v_mad_i64_i32 v[10:11], s[36:37], v10, s33, v[8:9]
	global_load_dword v138, v[10:11], off
.LBB0_303:
	s_or_b64 exec, exec, s[12:13]
	s_and_b64 vcc, exec, s[2:3]
	s_cbranch_vccnz .LBB0_305
	s_ashr_i32 s11, s10, 31
	v_lshl_add_u64 v[76:77], s[10:11], 0, v[2:3]
	v_lshl_add_u64 v[76:77], v[76:77], 2, s[16:17]
	global_load_dword v170, v[76:77], off offset:16
.LBB0_305:
	v_mov_b32_e32 v139, 0
	s_and_saveexec_b64 s[12:13], s[4:5]
	s_cbranch_execz .LBB0_307
	v_or_b32_e32 v10, s10, v21
	v_mad_i64_i32 v[10:11], s[36:37], v10, s33, v[8:9]
	global_load_dword v139, v[10:11], off
.LBB0_307:
	s_or_b64 exec, exec, s[12:13]
	s_and_b64 vcc, exec, s[2:3]
	s_cbranch_vccnz .LBB0_309
	s_ashr_i32 s11, s10, 31
	v_lshl_add_u64 v[76:77], s[10:11], 0, v[2:3]
	v_lshl_add_u64 v[76:77], v[76:77], 2, s[16:17]
	global_load_dword v171, v[76:77], off offset:24
.LBB0_309:
	v_mov_b32_e32 v140, 0
	s_and_saveexec_b64 s[12:13], s[4:5]
	s_cbranch_execz .LBB0_311
	v_or_b32_e32 v10, s10, v22
	v_mad_i64_i32 v[10:11], s[36:37], v10, s33, v[8:9]
	global_load_dword v140, v[10:11], off
.LBB0_311:
	s_or_b64 exec, exec, s[12:13]
	s_and_b64 vcc, exec, s[2:3]
	s_cbranch_vccnz .LBB0_313
	s_ashr_i32 s11, s10, 31
	v_lshl_add_u64 v[76:77], s[10:11], 0, v[2:3]
	v_lshl_add_u64 v[76:77], v[76:77], 2, s[16:17]
	global_load_dword v172, v[76:77], off offset:32
.LBB0_313:
	v_mov_b32_e32 v141, 0
	s_and_saveexec_b64 s[12:13], s[4:5]
	s_cbranch_execz .LBB0_315
	v_or_b32_e32 v10, s10, v23
	v_mad_i64_i32 v[10:11], s[36:37], v10, s33, v[8:9]
	global_load_dword v141, v[10:11], off
.LBB0_315:
	s_or_b64 exec, exec, s[12:13]
	s_and_b64 vcc, exec, s[2:3]
	s_cbranch_vccnz .LBB0_317
	s_ashr_i32 s11, s10, 31
	v_lshl_add_u64 v[76:77], s[10:11], 0, v[2:3]
	v_lshl_add_u64 v[76:77], v[76:77], 2, s[16:17]
	global_load_dword v173, v[76:77], off offset:40
.LBB0_317:
	v_mov_b32_e32 v142, 0
	s_and_saveexec_b64 s[12:13], s[4:5]
	s_cbranch_execz .LBB0_319
	v_or_b32_e32 v10, s10, v24
	v_mad_i64_i32 v[10:11], s[36:37], v10, s33, v[8:9]
	global_load_dword v142, v[10:11], off
.LBB0_319:
	s_or_b64 exec, exec, s[12:13]
	s_and_b64 vcc, exec, s[2:3]
	s_cbranch_vccnz .LBB0_321
	s_ashr_i32 s11, s10, 31
	v_lshl_add_u64 v[76:77], s[10:11], 0, v[2:3]
	v_lshl_add_u64 v[76:77], v[76:77], 2, s[16:17]
	global_load_dword v174, v[76:77], off offset:48
.LBB0_321:
	v_mov_b32_e32 v143, 0
	s_and_saveexec_b64 s[12:13], s[4:5]
	s_cbranch_execz .LBB0_323
	v_or_b32_e32 v10, s10, v25
	v_mad_i64_i32 v[10:11], s[36:37], v10, s33, v[8:9]
	global_load_dword v143, v[10:11], off
.LBB0_323:
	s_or_b64 exec, exec, s[12:13]
	s_and_b64 vcc, exec, s[2:3]
	s_cbranch_vccnz .LBB0_325
	s_ashr_i32 s11, s10, 31
	v_lshl_add_u64 v[76:77], s[10:11], 0, v[2:3]
	v_lshl_add_u64 v[76:77], v[76:77], 2, s[16:17]
	global_load_dword v175, v[76:77], off offset:56
.LBB0_325:
	v_mov_b32_e32 v144, 0
	s_and_saveexec_b64 s[12:13], s[4:5]
	s_cbranch_execz .LBB0_327
	v_or_b32_e32 v10, s10, v27
	v_mad_i64_i32 v[10:11], s[36:37], v10, s33, v[8:9]
	global_load_dword v144, v[10:11], off
.LBB0_327:
	s_or_b64 exec, exec, s[12:13]
	s_and_b64 vcc, exec, s[2:3]
	s_cbranch_vccnz .LBB0_329
	s_ashr_i32 s11, s10, 31
	v_lshl_add_u64 v[76:77], s[10:11], 0, v[2:3]
	v_lshl_add_u64 v[76:77], v[76:77], 2, s[16:17]
	global_load_dword v176, v[76:77], off offset:64
.LBB0_329:
	v_mov_b32_e32 v145, 0
	s_and_saveexec_b64 s[12:13], s[4:5]
	s_cbranch_execz .LBB0_331
	v_or_b32_e32 v10, s10, v28
	v_mad_i64_i32 v[10:11], s[36:37], v10, s33, v[8:9]
	global_load_dword v145, v[10:11], off
.LBB0_331:
	s_or_b64 exec, exec, s[12:13]
	s_and_b64 vcc, exec, s[2:3]
	s_cbranch_vccnz .LBB0_333
	s_ashr_i32 s11, s10, 31
	v_lshl_add_u64 v[76:77], s[10:11], 0, v[2:3]
	v_lshl_add_u64 v[76:77], v[76:77], 2, s[16:17]
	global_load_dword v177, v[76:77], off offset:72
.LBB0_333:
	v_mov_b32_e32 v146, 0
	s_and_saveexec_b64 s[12:13], s[4:5]
	s_cbranch_execz .LBB0_335
	v_or_b32_e32 v10, s10, v29
	v_mad_i64_i32 v[10:11], s[36:37], v10, s33, v[8:9]
	global_load_dword v146, v[10:11], off
.LBB0_335:
	s_or_b64 exec, exec, s[12:13]
	s_and_b64 vcc, exec, s[2:3]
	s_cbranch_vccnz .LBB0_337
	s_ashr_i32 s11, s10, 31
	v_lshl_add_u64 v[76:77], s[10:11], 0, v[2:3]
	v_lshl_add_u64 v[76:77], v[76:77], 2, s[16:17]
	global_load_dword v178, v[76:77], off offset:80
; #define LDS_WAIT() asm volatile("s_waitcnt lgkmcnt(0)" ::: "memory")
; __device__ __forceinline__ void transpose_mat(const float* __restrict__ W, int K, int N, int Npad, bf16_t* __restrict__ WT, int blk_mul, int blk_off,
;                                               LAS float* scr, int gw, int NGW, int lane, const float* __restrict__ gk = nullptr) {
;     ...
;         const int kb = it / nblk, nb = it % nblk, k0 = 64 * kb, n0 = 32 * nb;
;         const int ncol = n0 + (lane & 31);
; #pragma unroll
;         for (int i = 0; i < 32; ++i) { const int kk = 2 * i + (lane >> 5); float w = (ncol < N) ? W[(size_t)(k0 + kk) * N + ncol] : 0.f; if (gk) w *= gk[k0 + kk]; scr[kk * 33 + (lane & 31)] = w; }
;         LDS_WAIT();
.LBB0_337:
	v_mov_b32_e32 v147, 0
	s_and_saveexec_b64 s[12:13], s[4:5]
	s_cbranch_execz .LBB0_339
	v_or_b32_e32 v10, s10, v30
	v_mad_i64_i32 v[10:11], s[36:37], v10, s33, v[8:9]
	global_load_dword v147, v[10:11], off
.LBB0_339:
	s_or_b64 exec, exec, s[12:13]
	s_and_b64 vcc, exec, s[2:3]
	s_cbranch_vccnz .LBB0_341
	s_ashr_i32 s11, s10, 31
	v_lshl_add_u64 v[76:77], s[10:11], 0, v[2:3]
	v_lshl_add_u64 v[76:77], v[76:77], 2, s[16:17]
	global_load_dword v179, v[76:77], off offset:88
.LBB0_341:
	v_mov_b32_e32 v148, 0
	s_and_saveexec_b64 s[12:13], s[4:5]
	s_cbranch_execz .LBB0_343
	v_or_b32_e32 v10, s10, v31
	v_mad_i64_i32 v[10:11], s[36:37], v10, s33, v[8:9]
	global_load_dword v148, v[10:11], off
.LBB0_343:
	s_or_b64 exec, exec, s[12:13]
	s_and_b64 vcc, exec, s[2:3]
	s_cbranch_vccnz .LBB0_345
	s_ashr_i32 s11, s10, 31
	v_lshl_add_u64 v[76:77], s[10:11], 0, v[2:3]
	v_lshl_add_u64 v[76:77], v[76:77], 2, s[16:17]
	global_load_dword v180, v[76:77], off offset:96
.LBB0_345:
	v_mov_b32_e32 v149, 0
	s_and_saveexec_b64 s[12:13], s[4:5]
	s_cbranch_execz .LBB0_347
	v_or_b32_e32 v10, s10, v32
	v_mad_i64_i32 v[10:11], s[36:37], v10, s33, v[8:9]
	global_load_dword v149, v[10:11], off
.LBB0_347:
	s_or_b64 exec, exec, s[12:13]
	s_and_b64 vcc, exec, s[2:3]
	s_cbranch_vccnz .LBB0_349
	s_ashr_i32 s11, s10, 31
	v_lshl_add_u64 v[76:77], s[10:11], 0, v[2:3]
	v_lshl_add_u64 v[76:77], v[76:77], 2, s[16:17]
	global_load_dword v181, v[76:77], off offset:104
.LBB0_349:
	v_mov_b32_e32 v150, 0
	s_and_saveexec_b64 s[12:13], s[4:5]
	s_cbranch_execz .LBB0_351
	v_or_b32_e32 v10, s10, v33
	v_mad_i64_i32 v[10:11], s[36:37], v10, s33, v[8:9]
	global_load_dword v150, v[10:11], off
.LBB0_351:
	s_or_b64 exec, exec, s[12:13]
	s_and_b64 vcc, exec, s[2:3]
	s_cbranch_vccnz .LBB0_353
	s_ashr_i32 s11, s10, 31
	v_lshl_add_u64 v[76:77], s[10:11], 0, v[2:3]
	v_lshl_add_u64 v[76:77], v[76:77], 2, s[16:17]
	global_load_dword v182, v[76:77], off offset:112
.LBB0_353:
	v_mov_b32_e32 v151, 0
	s_and_saveexec_b64 s[12:13], s[4:5]
	s_cbranch_execz .LBB0_355
	v_or_b32_e32 v10, s10, v34
	v_mad_i64_i32 v[10:11], s[36:37], v10, s33, v[8:9]
	global_load_dword v151, v[10:11], off
.LBB0_355:
	s_or_b64 exec, exec, s[12:13]
	s_and_b64 vcc, exec, s[2:3]
	s_cbranch_vccnz .LBB0_357
	s_ashr_i32 s11, s10, 31
	v_lshl_add_u64 v[76:77], s[10:11], 0, v[2:3]
	v_lshl_add_u64 v[76:77], v[76:77], 2, s[16:17]
	global_load_dword v183, v[76:77], off offset:120
.LBB0_357:
	s_waitcnt vmcnt(0)
	s_and_b64 vcc, exec, s[2:3]
	s_cbranch_vccnz .Ltp2_nomul_1
	v_mul_f32_e32 v136, v136, v168
	v_mul_f32_e32 v137, v137, v169
	v_mul_f32_e32 v138, v138, v170
	v_mul_f32_e32 v139, v139, v171
	v_mul_f32_e32 v140, v140, v172
	v_mul_f32_e32 v141, v141, v173
	v_mul_f32_e32 v142, v142, v174
	v_mul_f32_e32 v143, v143, v175
	v_mul_f32_e32 v144, v144, v176
	v_mul_f32_e32 v145, v145, v177
	v_mul_f32_e32 v146, v146, v178
	v_mul_f32_e32 v147, v147, v179
	v_mul_f32_e32 v148, v148, v180
	v_mul_f32_e32 v149, v149, v181
	v_mul_f32_e32 v150, v150, v182
	v_mul_f32_e32 v151, v151, v183
.Ltp2_nomul_1:
	ds_write_b32 v14, v136
	ds_write_b32 v5, v137
	ds_write_b32 v12, v138
	ds_write_b32 v13, v139
	ds_write_b32 v15, v140
	ds_write_b32 v69, v141
	ds_write_b32 v70, v142
	ds_write_b32 v71, v143
	ds_write_b32 v68, v144
	ds_write_b32 v72, v145
	ds_write_b32 v73, v146
	ds_write_b32 v74, v147
	v_add_u32_e32 v11, v51, v55
	ds_write_b32 v11, v148
	v_add_u32_e32 v11, v51, v57
	ds_write_b32 v11, v149
	v_add_u32_e32 v11, v51, v58
	ds_write_b32 v11, v150
	v_add_u32_e32 v11, v51, v59
	ds_write_b32 v11, v151
	v_mov_b32_e32 v152, 0
	s_and_saveexec_b64 s[12:13], s[4:5]
	s_cbranch_execz .LBB0_359
	v_or_b32_e32 v10, s10, v35
	v_mad_i64_i32 v[10:11], s[36:37], v10, s33, v[8:9]
	global_load_dword v152, v[10:11], off
.LBB0_359:
	s_or_b64 exec, exec, s[12:13]
	s_and_b64 vcc, exec, s[2:3]
	s_cbranch_vccnz .LBB0_361
	s_ashr_i32 s11, s10, 31
	v_lshl_add_u64 v[76:77], s[10:11], 0, v[2:3]
	v_lshl_add_u64 v[76:77], v[76:77], 2, s[16:17]
	global_load_dword v184, v[76:77], off offset:128
.LBB0_361:
	v_mov_b32_e32 v153, 0
	s_and_saveexec_b64 s[12:13], s[4:5]
	s_cbranch_execz .LBB0_363
	v_or_b32_e32 v10, s10, v36
	v_mad_i64_i32 v[10:11], s[36:37], v10, s33, v[8:9]
	global_load_dword v153, v[10:11], off
.LBB0_363:
	s_or_b64 exec, exec, s[12:13]
	s_and_b64 vcc, exec, s[2:3]
	s_cbranch_vccnz .LBB0_365
	s_ashr_i32 s11, s10, 31
	v_lshl_add_u64 v[76:77], s[10:11], 0, v[2:3]
	v_lshl_add_u64 v[76:77], v[76:77], 2, s[16:17]
	global_load_dword v185, v[76:77], off offset:136
.LBB0_365:
	v_mov_b32_e32 v154, 0
	s_and_saveexec_b64 s[12:13], s[4:5]
	s_cbranch_execz .LBB0_367
	v_or_b32_e32 v10, s10, v37
	v_mad_i64_i32 v[10:11], s[36:37], v10, s33, v[8:9]
	global_load_dword v154, v[10:11], off
.LBB0_367:
	s_or_b64 exec, exec, s[12:13]
	s_and_b64 vcc, exec, s[2:3]
	s_cbranch_vccnz .LBB0_369
	s_ashr_i32 s11, s10, 31
	v_lshl_add_u64 v[76:77], s[10:11], 0, v[2:3]
	v_lshl_add_u64 v[76:77], v[76:77], 2, s[16:17]
	global_load_dword v186, v[76:77], off offset:144
.LBB0_369:
	v_mov_b32_e32 v155, 0
	s_and_saveexec_b64 s[12:13], s[4:5]
	s_cbranch_execz .LBB0_371
	v_or_b32_e32 v10, s10, v38
	v_mad_i64_i32 v[10:11], s[36:37], v10, s33, v[8:9]
	global_load_dword v155, v[10:11], off
.LBB0_371:
	s_or_b64 exec, exec, s[12:13]
	s_and_b64 vcc, exec, s[2:3]
	s_cbranch_vccnz .LBB0_373
	s_ashr_i32 s11, s10, 31
	v_lshl_add_u64 v[76:77], s[10:11], 0, v[2:3]
	v_lshl_add_u64 v[76:77], v[76:77], 2, s[16:17]
	global_load_dword v187, v[76:77], off offset:152
.LBB0_373:
	v_mov_b32_e32 v156, 0
	s_and_saveexec_b64 s[12:13], s[4:5]
	s_cbranch_execz .LBB0_375
	v_or_b32_e32 v10, s10, v39
	v_mad_i64_i32 v[10:11], s[36:37], v10, s33, v[8:9]
	global_load_dword v156, v[10:11], off
; #define LDS_WAIT() asm volatile("s_waitcnt lgkmcnt(0)" ::: "memory")
; __device__ __forceinline__ void transpose_mat(const float* __restrict__ W, int K, int N, int Npad, bf16_t* __restrict__ WT, int blk_mul, int blk_off,
;                                               LAS float* scr, int gw, int NGW, int lane, const float* __restrict__ gk = nullptr) {
;     ...
;         const int kb = it / nblk, nb = it % nblk, k0 = 64 * kb, n0 = 32 * nb;
;         const int ncol = n0 + (lane & 31);
; #pragma unroll
;         for (int i = 0; i < 32; ++i) { const int kk = 2 * i + (lane >> 5); float w = (ncol < N) ? W[(size_t)(k0 + kk) * N + ncol] : 0.f; if (gk) w *= gk[k0 + kk]; scr[kk * 33 + (lane & 31)] = w; }
;         LDS_WAIT();
.LBB0_375:
	s_or_b64 exec, exec, s[12:13]
	s_and_b64 vcc, exec, s[2:3]
	s_cbranch_vccnz .LBB0_377
	s_ashr_i32 s11, s10, 31
	v_lshl_add_u64 v[76:77], s[10:11], 0, v[2:3]
	v_lshl_add_u64 v[76:77], v[76:77], 2, s[16:17]
	global_load_dword v188, v[76:77], off offset:160
.LBB0_377:
	v_mov_b32_e32 v157, 0
	s_and_saveexec_b64 s[12:13], s[4:5]
	s_cbranch_execz .LBB0_379
	v_or_b32_e32 v10, s10, v40
	v_mad_i64_i32 v[10:11], s[36:37], v10, s33, v[8:9]
	global_load_dword v157, v[10:11], off
.LBB0_379:
	s_or_b64 exec, exec, s[12:13]
	s_and_b64 vcc, exec, s[2:3]
	s_cbranch_vccnz .LBB0_381
	s_ashr_i32 s11, s10, 31
	v_lshl_add_u64 v[76:77], s[10:11], 0, v[2:3]
	v_lshl_add_u64 v[76:77], v[76:77], 2, s[16:17]
	global_load_dword v189, v[76:77], off offset:168
.LBB0_381:
	v_mov_b32_e32 v158, 0
	s_and_saveexec_b64 s[12:13], s[4:5]
	s_cbranch_execz .LBB0_383
	v_or_b32_e32 v10, s10, v41
	v_mad_i64_i32 v[10:11], s[36:37], v10, s33, v[8:9]
	global_load_dword v158, v[10:11], off
.LBB0_383:
	s_or_b64 exec, exec, s[12:13]
	s_and_b64 vcc, exec, s[2:3]
	s_cbranch_vccnz .LBB0_385
	s_ashr_i32 s11, s10, 31
	v_lshl_add_u64 v[76:77], s[10:11], 0, v[2:3]
	v_lshl_add_u64 v[76:77], v[76:77], 2, s[16:17]
	global_load_dword v190, v[76:77], off offset:176
.LBB0_385:
	v_mov_b32_e32 v159, 0
	s_and_saveexec_b64 s[12:13], s[4:5]
	s_cbranch_execz .LBB0_387
	v_or_b32_e32 v10, s10, v42
	v_mad_i64_i32 v[10:11], s[36:37], v10, s33, v[8:9]
	global_load_dword v159, v[10:11], off
.LBB0_387:
	s_or_b64 exec, exec, s[12:13]
	s_and_b64 vcc, exec, s[2:3]
	s_cbranch_vccnz .LBB0_389
	s_ashr_i32 s11, s10, 31
	v_lshl_add_u64 v[76:77], s[10:11], 0, v[2:3]
	v_lshl_add_u64 v[76:77], v[76:77], 2, s[16:17]
	global_load_dword v191, v[76:77], off offset:184
.LBB0_389:
	v_mov_b32_e32 v160, 0
	s_and_saveexec_b64 s[12:13], s[4:5]
	s_cbranch_execz .LBB0_391
	v_or_b32_e32 v10, s10, v43
	v_mad_i64_i32 v[10:11], s[36:37], v10, s33, v[8:9]
	global_load_dword v160, v[10:11], off
.LBB0_391:
	s_or_b64 exec, exec, s[12:13]
	s_and_b64 vcc, exec, s[2:3]
	s_cbranch_vccnz .LBB0_393
	s_ashr_i32 s11, s10, 31
	v_lshl_add_u64 v[76:77], s[10:11], 0, v[2:3]
	v_lshl_add_u64 v[76:77], v[76:77], 2, s[16:17]
	global_load_dword v192, v[76:77], off offset:192
.LBB0_393:
	v_mov_b32_e32 v161, 0
	s_and_saveexec_b64 s[12:13], s[4:5]
	s_cbranch_execz .LBB0_395
	v_or_b32_e32 v10, s10, v44
	v_mad_i64_i32 v[10:11], s[36:37], v10, s33, v[8:9]
	global_load_dword v161, v[10:11], off
.LBB0_395:
	s_or_b64 exec, exec, s[12:13]
	s_and_b64 vcc, exec, s[2:3]
	s_cbranch_vccnz .LBB0_397
	s_ashr_i32 s11, s10, 31
	v_lshl_add_u64 v[76:77], s[10:11], 0, v[2:3]
	v_lshl_add_u64 v[76:77], v[76:77], 2, s[16:17]
	global_load_dword v193, v[76:77], off offset:200
.LBB0_397:
	v_mov_b32_e32 v162, 0
	s_and_saveexec_b64 s[12:13], s[4:5]
	s_cbranch_execz .LBB0_399
	v_or_b32_e32 v10, s10, v45
	v_mad_i64_i32 v[10:11], s[36:37], v10, s33, v[8:9]
	global_load_dword v162, v[10:11], off
.LBB0_399:
	s_or_b64 exec, exec, s[12:13]
	s_and_b64 vcc, exec, s[2:3]
	s_cbranch_vccnz .LBB0_401
	s_ashr_i32 s11, s10, 31
	v_lshl_add_u64 v[76:77], s[10:11], 0, v[2:3]
	v_lshl_add_u64 v[76:77], v[76:77], 2, s[16:17]
	global_load_dword v194, v[76:77], off offset:208
.LBB0_401:
	v_mov_b32_e32 v163, 0
	s_and_saveexec_b64 s[12:13], s[4:5]
	s_cbranch_execz .LBB0_403
	v_or_b32_e32 v11, s10, v46
	v_mad_i64_i32 v[76:77], s[36:37], v11, s33, v[8:9]
	global_load_dword v163, v[76:77], off
.LBB0_403:
	s_or_b64 exec, exec, s[12:13]
	s_and_b64 vcc, exec, s[2:3]
	s_cbranch_vccnz .LBB0_405
	s_ashr_i32 s11, s10, 31
	v_lshl_add_u64 v[76:77], s[10:11], 0, v[2:3]
	v_lshl_add_u64 v[76:77], v[76:77], 2, s[16:17]
	global_load_dword v195, v[76:77], off offset:216
.LBB0_405:
	v_mov_b32_e32 v164, 0
	s_and_saveexec_b64 s[12:13], s[4:5]
	s_cbranch_execz .LBB0_407
	v_or_b32_e32 v11, s10, v47
	v_mad_i64_i32 v[76:77], s[36:37], v11, s33, v[8:9]
	global_load_dword v164, v[76:77], off
.LBB0_407:
	s_or_b64 exec, exec, s[12:13]
	s_and_b64 vcc, exec, s[2:3]
	s_cbranch_vccnz .LBB0_409
	s_ashr_i32 s11, s10, 31
	v_lshl_add_u64 v[76:77], s[10:11], 0, v[2:3]
	v_lshl_add_u64 v[76:77], v[76:77], 2, s[16:17]
	global_load_dword v196, v[76:77], off offset:224
.LBB0_409:
	v_mov_b32_e32 v165, 0
	s_and_saveexec_b64 s[12:13], s[4:5]
	s_cbranch_execz .LBB0_411
	v_or_b32_e32 v11, s10, v48
	v_mad_i64_i32 v[76:77], s[36:37], v11, s33, v[8:9]
	global_load_dword v165, v[76:77], off
.LBB0_411:
	s_or_b64 exec, exec, s[12:13]
	s_and_b64 vcc, exec, s[2:3]
	s_cbranch_vccnz .LBB0_413
	s_ashr_i32 s11, s10, 31
	v_lshl_add_u64 v[76:77], s[10:11], 0, v[2:3]
	v_lshl_add_u64 v[76:77], v[76:77], 2, s[16:17]
	global_load_dword v197, v[76:77], off offset:232
.LBB0_413:
	v_mov_b32_e32 v166, 0
	s_and_saveexec_b64 s[12:13], s[4:5]
	s_cbranch_execz .LBB0_415
	v_or_b32_e32 v11, s10, v49
	v_mad_i64_i32 v[76:77], s[36:37], v11, s33, v[8:9]
	global_load_dword v166, v[76:77], off
.LBB0_415:
	s_or_b64 exec, exec, s[12:13]
	s_and_b64 vcc, exec, s[2:3]
	s_cbranch_vccnz .LBB0_417
	s_ashr_i32 s11, s10, 31
	v_lshl_add_u64 v[76:77], s[10:11], 0, v[2:3]
	v_lshl_add_u64 v[76:77], v[76:77], 2, s[16:17]
	global_load_dword v198, v[76:77], off offset:240
.LBB0_417:
	v_mov_b32_e32 v167, 0
	s_and_saveexec_b64 s[12:13], s[4:5]
	s_cbranch_execz .LBB0_419
	v_or_b32_e32 v11, s10, v50
	v_mad_i64_i32 v[8:9], s[4:5], v11, s33, v[8:9]
	global_load_dword v167, v[8:9], off
.LBB0_419:
	s_or_b64 exec, exec, s[12:13]
	s_and_b64 vcc, exec, s[8:9]
	s_cbranch_vccz .LBB0_421
	s_ashr_i32 s11, s10, 31
	v_lshl_add_u64 v[8:9], s[10:11], 0, v[2:3]
	v_lshl_add_u64 v[8:9], v[8:9], 2, s[16:17]
	global_load_dword v199, v[8:9], off offset:248
.LBB0_421:
.LBB0_422:
	s_ashr_i32 s11, s10, 31
	v_mov_b32_e32 v8, v11
	s_waitcnt vmcnt(0)
	s_and_b64 vcc, exec, s[8:9]
	s_cbranch_vccz .Ltp2_nomul_2
	v_mul_f32_e32 v152, v152, v184
	v_mul_f32_e32 v153, v153, v185
	v_mul_f32_e32 v154, v154, v186
	v_mul_f32_e32 v155, v155, v187
	v_mul_f32_e32 v156, v156, v188
	v_mul_f32_e32 v157, v157, v189
	v_mul_f32_e32 v158, v158, v190
	v_mul_f32_e32 v159, v159, v191
	v_mul_f32_e32 v160, v160, v192
	v_mul_f32_e32 v161, v161, v193
	v_mul_f32_e32 v162, v162, v194
	v_mul_f32_e32 v163, v163, v195
	v_mul_f32_e32 v164, v164, v196
	v_mul_f32_e32 v165, v165, v197
	v_mul_f32_e32 v166, v166, v198
	v_mul_f32_e32 v167, v167, v199
.Ltp2_nomul_2:
	v_add_u32_e32 v11, v51, v56
	ds_write_b32 v11, v152
	v_add_u32_e32 v11, v51, v60
	ds_write_b32 v11, v153
	v_add_u32_e32 v11, v51, v61
	ds_write_b32 v11, v154
	v_add_u32_e32 v11, v51, v62
	ds_write_b32 v11, v155
	v_add_u32_e32 v11, v51, v52
	ds_write_b32 v11, v156
	v_add_u32_e32 v11, v51, v63
	ds_write_b32 v11, v157
	v_add_u32_e32 v11, v51, v64
	ds_write_b32 v11, v158
	v_add_u32_e32 v11, v51, v65
	ds_write_b32 v11, v159
	v_add_u32_e32 v11, v51, v53
	ds_write_b32 v11, v160
	v_add_u32_e32 v11, v51, v67
	ds_write_b32 v11, v161
	v_add_u32_e32 v10, v51, v54
	ds_write_b32 v10, v162
	ds_write_b32 v10, v163 offset:264
	ds_write_b32 v10, v164 offset:528
	ds_write_b32 v10, v165 offset:792
	ds_write_b32 v10, v166 offset:1056
	v_mov_b32_e32 v8, v167
	s_branch .LBB0_292

; #define LAS __attribute__((address_space(3)))
; __device__ __forceinline__ void transpose_mat(const float* __restrict__ W, int K, int N, int Npad, bf16_t* __restrict__ WT, int blk_mul, int blk_off,
;                                               LAS float* scr, int gw, int NGW, int lane, const float* __restrict__ gk = nullptr) {
;     ...
;         const int kb = it / nblk, nb = it % nblk, k0 = 64 * kb, n0 = 32 * nb;
;         const int ncol = n0 + (lane & 31);
; #pragma unroll
;         for (int i = 0; i < 32; ++i) { const int kk = 2 * i + (lane >> 5); float w = (ncol < N) ? W[(size_t)(k0 + kk) * N + ncol] : 0.f; if (gk) w *= gk[k0 + kk]; scr[kk * 33 + (lane & 31)] = w; }
; __global__ void __launch_bounds__(NTHR, 2) hymba_fwd(KArgs a) {
;     ...
;             convert_layer(1, PIN(2), PIN(3), PIN(4), PIN(1), PIN(6), PIN(5), PIN(18), PIN(8), PIN(10), PIN(14), PIN(16), ws, (LAS float*)(lds + wave * 16384), (bid - cfirst) * 8 + wave, (G - cfirst) * 8, lane_);
.LBB0_2451:
	s_mul_hi_i32 s4, s26, 0x2e8ba2e9
	s_lshr_b32 s5, s4, 31
	s_ashr_i32 s27, s4, 4
	s_add_i32 s27, s27, s5
	s_mul_i32 s28, s27, 0xfffff500
	s_add_i32 s4, s28, s15
	v_add_u32_e32 v34, s4, v100
	s_lshl_b32 s18, s27, 6
	s_movk_i32 s4, 0xb00
	v_ashrrev_i32_e32 v35, 31, v34
	v_cmp_gt_i32_e64 s[4:5], s4, v34
	v_lshl_add_u64 v[34:35], v[34:35], 2, v[30:31]
	v_mov_b32_e32 v136, 0
	v_or_b32_e32 v36, s18, v16
	s_and_saveexec_b64 s[6:7], s[4:5]
	s_cbranch_execz .LBB0_2453
	v_mad_i64_i32 v[102:103], s[20:21], v36, s70, v[34:35]
	global_load_dword v136, v[102:103], off
.LBB0_2453:
	s_or_b64 exec, exec, s[6:7]
	v_cndmask_b32_e64 v37, 0, 1, s[2:3]
	v_cmp_ne_u32_e64 s[6:7], 1, v37
	s_andn2_b64 vcc, exec, s[2:3]
	s_cbranch_vccnz .LBB0_2455
	v_ashrrev_i32_e32 v37, 31, v36
	v_lshl_add_u64 v[36:37], v[36:37], 2, v[28:29]
	global_load_dword v168, v[36:37], off
.LBB0_2455:
	v_mov_b32_e32 v137, 0
	s_and_saveexec_b64 s[20:21], s[4:5]
	s_cbranch_execz .LBB0_2457
	v_or_b32_e32 v36, s18, v41
	v_mad_i64_i32 v[36:37], s[30:31], v36, s70, v[34:35]
	global_load_dword v137, v[36:37], off
.LBB0_2457:
	s_or_b64 exec, exec, s[20:21]
	s_and_b64 vcc, exec, s[6:7]
	s_cbranch_vccnz .LBB0_2459
	s_ashr_i32 s19, s18, 31
	v_lshl_add_u64 v[102:103], s[18:19], 0, v[16:17]
	v_lshl_add_u64 v[102:103], v[102:103], 2, v[28:29]
	global_load_dword v169, v[102:103], off offset:8
.LBB0_2459:
	v_mov_b32_e32 v138, 0
	s_and_saveexec_b64 s[20:21], s[4:5]
	s_cbranch_execz .LBB0_2461
	v_or_b32_e32 v36, s18, v42
	v_mad_i64_i32 v[36:37], s[30:31], v36, s70, v[34:35]
	global_load_dword v138, v[36:37], off
.LBB0_2461:
	s_or_b64 exec, exec, s[20:21]
	s_and_b64 vcc, exec, s[6:7]
	s_cbranch_vccnz .LBB0_2463
	s_ashr_i32 s19, s18, 31
	v_lshl_add_u64 v[102:103], s[18:19], 0, v[16:17]
	v_lshl_add_u64 v[102:103], v[102:103], 2, v[28:29]
	global_load_dword v170, v[102:103], off offset:16
.LBB0_2463:
	v_mov_b32_e32 v139, 0
	s_and_saveexec_b64 s[20:21], s[4:5]
	s_cbranch_execz .LBB0_2465
	v_or_b32_e32 v36, s18, v43
	v_mad_i64_i32 v[36:37], s[30:31], v36, s70, v[34:35]
	global_load_dword v139, v[36:37], off
.LBB0_2465:
	s_or_b64 exec, exec, s[20:21]
	s_and_b64 vcc, exec, s[6:7]
	s_cbranch_vccnz .LBB0_2467
	s_ashr_i32 s19, s18, 31
	v_lshl_add_u64 v[102:103], s[18:19], 0, v[16:17]
	v_lshl_add_u64 v[102:103], v[102:103], 2, v[28:29]
	global_load_dword v171, v[102:103], off offset:24
.LBB0_2467:
	v_mov_b32_e32 v140, 0
	s_and_saveexec_b64 s[20:21], s[4:5]
	s_cbranch_execz .LBB0_2469
	v_or_b32_e32 v36, s18, v44
	v_mad_i64_i32 v[36:37], s[30:31], v36, s70, v[34:35]
	global_load_dword v140, v[36:37], off
.LBB0_2469:
	s_or_b64 exec, exec, s[20:21]
	s_and_b64 vcc, exec, s[6:7]
	s_cbranch_vccnz .LBB0_2471
	s_ashr_i32 s19, s18, 31
	v_lshl_add_u64 v[102:103], s[18:19], 0, v[16:17]
	v_lshl_add_u64 v[102:103], v[102:103], 2, v[28:29]
	global_load_dword v172, v[102:103], off offset:32
.LBB0_2471:
	v_mov_b32_e32 v141, 0
	s_and_saveexec_b64 s[20:21], s[4:5]
	s_cbranch_execz .LBB0_2473
	v_or_b32_e32 v36, s18, v46
	v_mad_i64_i32 v[36:37], s[30:31], v36, s70, v[34:35]
	global_load_dword v141, v[36:37], off
.LBB0_2473:
	s_or_b64 exec, exec, s[20:21]
	s_and_b64 vcc, exec, s[6:7]
	s_cbranch_vccnz .LBB0_2475
	s_ashr_i32 s19, s18, 31
	v_lshl_add_u64 v[102:103], s[18:19], 0, v[16:17]
	v_lshl_add_u64 v[102:103], v[102:103], 2, v[28:29]
	global_load_dword v173, v[102:103], off offset:40
.LBB0_2475:
	v_mov_b32_e32 v142, 0
	s_and_saveexec_b64 s[20:21], s[4:5]
	s_cbranch_execz .LBB0_2477
	v_or_b32_e32 v36, s18, v47
	v_mad_i64_i32 v[36:37], s[30:31], v36, s70, v[34:35]
	global_load_dword v142, v[36:37], off
.LBB0_2477:
	s_or_b64 exec, exec, s[20:21]
	s_and_b64 vcc, exec, s[6:7]
	s_cbranch_vccnz .LBB0_2479
	s_ashr_i32 s19, s18, 31
	v_lshl_add_u64 v[102:103], s[18:19], 0, v[16:17]
	v_lshl_add_u64 v[102:103], v[102:103], 2, v[28:29]
	global_load_dword v174, v[102:103], off offset:48
.LBB0_2479:
	v_mov_b32_e32 v143, 0
	s_and_saveexec_b64 s[20:21], s[4:5]
	s_cbranch_execz .LBB0_2481
	v_or_b32_e32 v36, s18, v48
	v_mad_i64_i32 v[36:37], s[30:31], v36, s70, v[34:35]
	global_load_dword v143, v[36:37], off
.LBB0_2481:
	s_or_b64 exec, exec, s[20:21]
	s_and_b64 vcc, exec, s[6:7]
	s_cbranch_vccnz .LBB0_2483
	s_ashr_i32 s19, s18, 31
	v_lshl_add_u64 v[102:103], s[18:19], 0, v[16:17]
	v_lshl_add_u64 v[102:103], v[102:103], 2, v[28:29]
	global_load_dword v175, v[102:103], off offset:56
.LBB0_2483:
	v_mov_b32_e32 v144, 0
	s_and_saveexec_b64 s[20:21], s[4:5]
	s_cbranch_execz .LBB0_2485
	v_or_b32_e32 v36, s18, v49
	v_mad_i64_i32 v[36:37], s[30:31], v36, s70, v[34:35]
	global_load_dword v144, v[36:37], off
.LBB0_2485:
	s_or_b64 exec, exec, s[20:21]
	s_and_b64 vcc, exec, s[6:7]
	s_cbranch_vccnz .LBB0_2487
	s_ashr_i32 s19, s18, 31
	v_lshl_add_u64 v[102:103], s[18:19], 0, v[16:17]
	v_lshl_add_u64 v[102:103], v[102:103], 2, v[28:29]
	global_load_dword v176, v[102:103], off offset:64
.LBB0_2487:
	v_mov_b32_e32 v145, 0
	s_and_saveexec_b64 s[20:21], s[4:5]
	s_cbranch_execz .LBB0_2489
	v_or_b32_e32 v36, s18, v51
	v_mad_i64_i32 v[36:37], s[30:31], v36, s70, v[34:35]
	global_load_dword v145, v[36:37], off
.LBB0_2489:
	s_or_b64 exec, exec, s[20:21]
	s_and_b64 vcc, exec, s[6:7]
	s_cbranch_vccnz .LBB0_2491
	s_ashr_i32 s19, s18, 31
	v_lshl_add_u64 v[102:103], s[18:19], 0, v[16:17]
	v_lshl_add_u64 v[102:103], v[102:103], 2, v[28:29]
	global_load_dword v177, v[102:103], off offset:72
.LBB0_2491:
	v_mov_b32_e32 v146, 0
	s_and_saveexec_b64 s[20:21], s[4:5]
	s_cbranch_execz .LBB0_2493
	v_or_b32_e32 v36, s18, v52
	v_mad_i64_i32 v[36:37], s[30:31], v36, s70, v[34:35]
	global_load_dword v146, v[36:37], off
; #define LDS_WAIT() asm volatile("s_waitcnt lgkmcnt(0)" ::: "memory")
; __device__ __forceinline__ void transpose_mat(const float* __restrict__ W, int K, int N, int Npad, bf16_t* __restrict__ WT, int blk_mul, int blk_off,
;                                               LAS float* scr, int gw, int NGW, int lane, const float* __restrict__ gk = nullptr) {
;     ...
;         const int kb = it / nblk, nb = it % nblk, k0 = 64 * kb, n0 = 32 * nb;
;         const int ncol = n0 + (lane & 31);
; #pragma unroll
;         for (int i = 0; i < 32; ++i) { const int kk = 2 * i + (lane >> 5); float w = (ncol < N) ? W[(size_t)(k0 + kk) * N + ncol] : 0.f; if (gk) w *= gk[k0 + kk]; scr[kk * 33 + (lane & 31)] = w; }
;         LDS_WAIT();
.LBB0_2493:
	s_or_b64 exec, exec, s[20:21]
	s_and_b64 vcc, exec, s[6:7]
	s_cbranch_vccnz .LBB0_2495
	s_ashr_i32 s19, s18, 31
	v_lshl_add_u64 v[102:103], s[18:19], 0, v[16:17]
	v_lshl_add_u64 v[102:103], v[102:103], 2, v[28:29]
	global_load_dword v178, v[102:103], off offset:80
.LBB0_2495:
	v_mov_b32_e32 v147, 0
	s_and_saveexec_b64 s[20:21], s[4:5]
	s_cbranch_execz .LBB0_2497
	v_or_b32_e32 v36, s18, v53
	v_mad_i64_i32 v[36:37], s[30:31], v36, s70, v[34:35]
	global_load_dword v147, v[36:37], off
.LBB0_2497:
	s_or_b64 exec, exec, s[20:21]
	s_and_b64 vcc, exec, s[6:7]
	s_cbranch_vccnz .LBB0_2499
	s_ashr_i32 s19, s18, 31
	v_lshl_add_u64 v[102:103], s[18:19], 0, v[16:17]
	v_lshl_add_u64 v[102:103], v[102:103], 2, v[28:29]
	global_load_dword v179, v[102:103], off offset:88
.LBB0_2499:
	v_mov_b32_e32 v148, 0
	s_and_saveexec_b64 s[20:21], s[4:5]
	s_cbranch_execz .LBB0_2501
	v_or_b32_e32 v36, s18, v54
	v_mad_i64_i32 v[36:37], s[30:31], v36, s70, v[34:35]
	global_load_dword v148, v[36:37], off
.LBB0_2501:
	s_or_b64 exec, exec, s[20:21]
	s_and_b64 vcc, exec, s[6:7]
	s_cbranch_vccnz .LBB0_2503
	s_ashr_i32 s19, s18, 31
	v_lshl_add_u64 v[102:103], s[18:19], 0, v[16:17]
	v_lshl_add_u64 v[102:103], v[102:103], 2, v[28:29]
	global_load_dword v180, v[102:103], off offset:96
.LBB0_2503:
	v_mov_b32_e32 v149, 0
	s_and_saveexec_b64 s[20:21], s[4:5]
	s_cbranch_execz .LBB0_2505
	v_or_b32_e32 v36, s18, v56
	v_mad_i64_i32 v[36:37], s[30:31], v36, s70, v[34:35]
	global_load_dword v149, v[36:37], off
.LBB0_2505:
	s_or_b64 exec, exec, s[20:21]
	s_and_b64 vcc, exec, s[6:7]
	s_cbranch_vccnz .LBB0_2507
	s_ashr_i32 s19, s18, 31
	v_lshl_add_u64 v[102:103], s[18:19], 0, v[16:17]
	v_lshl_add_u64 v[102:103], v[102:103], 2, v[28:29]
	global_load_dword v181, v[102:103], off offset:104
.LBB0_2507:
	v_mov_b32_e32 v150, 0
	s_and_saveexec_b64 s[20:21], s[4:5]
	s_cbranch_execz .LBB0_2509
	v_or_b32_e32 v36, s18, v57
	v_mad_i64_i32 v[36:37], s[30:31], v36, s70, v[34:35]
	global_load_dword v150, v[36:37], off
.LBB0_2509:
	s_or_b64 exec, exec, s[20:21]
	s_and_b64 vcc, exec, s[6:7]
	s_cbranch_vccnz .LBB0_2511
	s_ashr_i32 s19, s18, 31
	v_lshl_add_u64 v[102:103], s[18:19], 0, v[16:17]
	v_lshl_add_u64 v[102:103], v[102:103], 2, v[28:29]
	global_load_dword v182, v[102:103], off offset:112
.LBB0_2511:
	v_mov_b32_e32 v151, 0
	s_and_saveexec_b64 s[20:21], s[4:5]
	s_cbranch_execz .LBB0_2513
	v_or_b32_e32 v36, s18, v58
	v_mad_i64_i32 v[36:37], s[30:31], v36, s70, v[34:35]
	global_load_dword v151, v[36:37], off
.LBB0_2513:
	s_or_b64 exec, exec, s[20:21]
	s_and_b64 vcc, exec, s[6:7]
	s_cbranch_vccnz .LBB0_2515
	s_ashr_i32 s19, s18, 31
	v_lshl_add_u64 v[102:103], s[18:19], 0, v[16:17]
	v_lshl_add_u64 v[102:103], v[102:103], 2, v[28:29]
	global_load_dword v183, v[102:103], off offset:120
.LBB0_2515:
	s_waitcnt vmcnt(0)
	s_and_b64 vcc, exec, s[6:7]
	s_cbranch_vccnz .Ltp3_nomul_1
	v_mul_f32_e32 v136, v136, v168
	v_mul_f32_e32 v137, v137, v169
	v_mul_f32_e32 v138, v138, v170
	v_mul_f32_e32 v139, v139, v171
	v_mul_f32_e32 v140, v140, v172
	v_mul_f32_e32 v141, v141, v173
	v_mul_f32_e32 v142, v142, v174
	v_mul_f32_e32 v143, v143, v175
	v_mul_f32_e32 v144, v144, v176
	v_mul_f32_e32 v145, v145, v177
	v_mul_f32_e32 v146, v146, v178
	v_mul_f32_e32 v147, v147, v179
	v_mul_f32_e32 v148, v148, v180
	v_mul_f32_e32 v149, v149, v181
	v_mul_f32_e32 v150, v150, v182
	v_mul_f32_e32 v151, v151, v183
.Ltp3_nomul_1:
	v_add_u32_e32 v36, v39, v40
	ds_write_b32 v36, v136
	v_add_u32_e32 v37, v39, v80
	ds_write_b32 v37, v137
	v_add_u32_e32 v37, v39, v81
	ds_write_b32 v37, v138
	v_add_u32_e32 v37, v39, v82
	ds_write_b32 v37, v139
	v_add_u32_e32 v37, v39, v45
	ds_write_b32 v37, v140
	v_add_u32_e32 v37, v39, v83
	ds_write_b32 v37, v141
	v_add_u32_e32 v37, v39, v84
	ds_write_b32 v37, v142
	v_add_u32_e32 v37, v39, v85
	ds_write_b32 v37, v143
	v_add_u32_e32 v37, v39, v50
	ds_write_b32 v37, v144
	v_add_u32_e32 v37, v39, v86
	ds_write_b32 v37, v145
	v_add_u32_e32 v37, v39, v87
	ds_write_b32 v37, v146
	v_add_u32_e32 v37, v39, v88
	ds_write_b32 v37, v147
	v_add_u32_e32 v37, v39, v55
	ds_write_b32 v37, v148
	v_add_u32_e32 v37, v39, v89
	ds_write_b32 v37, v149
	v_add_u32_e32 v37, v39, v90
	ds_write_b32 v37, v150
	v_add_u32_e32 v37, v39, v91
	ds_write_b32 v37, v151
	v_mov_b32_e32 v152, 0
	s_and_saveexec_b64 s[20:21], s[4:5]
	s_cbranch_execz .LBB0_2517
	v_or_b32_e32 v36, s18, v59
	v_mad_i64_i32 v[36:37], s[30:31], v36, s70, v[34:35]
	global_load_dword v152, v[36:37], off
.LBB0_2517:
	s_or_b64 exec, exec, s[20:21]
	s_and_b64 vcc, exec, s[6:7]
	s_cbranch_vccnz .LBB0_2519
	s_ashr_i32 s19, s18, 31
	v_lshl_add_u64 v[102:103], s[18:19], 0, v[16:17]
	v_lshl_add_u64 v[102:103], v[102:103], 2, v[28:29]
	global_load_dword v184, v[102:103], off offset:128
.LBB0_2519:
	v_mov_b32_e32 v153, 0
	s_and_saveexec_b64 s[20:21], s[4:5]
	s_cbranch_execz .LBB0_2521
	v_or_b32_e32 v36, s18, v61
	v_mad_i64_i32 v[36:37], s[30:31], v36, s70, v[34:35]
	global_load_dword v153, v[36:37], off
.LBB0_2521:
	s_or_b64 exec, exec, s[20:21]
	s_and_b64 vcc, exec, s[6:7]
	s_cbranch_vccnz .LBB0_2523
	s_ashr_i32 s19, s18, 31
	v_lshl_add_u64 v[102:103], s[18:19], 0, v[16:17]
	v_lshl_add_u64 v[102:103], v[102:103], 2, v[28:29]
	global_load_dword v185, v[102:103], off offset:136
.LBB0_2523:
	v_mov_b32_e32 v154, 0
	s_and_saveexec_b64 s[20:21], s[4:5]
	s_cbranch_execz .LBB0_2525
	v_or_b32_e32 v36, s18, v62
	v_mad_i64_i32 v[36:37], s[30:31], v36, s70, v[34:35]
	global_load_dword v154, v[36:37], off
.LBB0_2525:
	s_or_b64 exec, exec, s[20:21]
	s_and_b64 vcc, exec, s[6:7]
	s_cbranch_vccnz .LBB0_2527
	s_ashr_i32 s19, s18, 31
	v_lshl_add_u64 v[102:103], s[18:19], 0, v[16:17]
	v_lshl_add_u64 v[102:103], v[102:103], 2, v[28:29]
	global_load_dword v186, v[102:103], off offset:144
; __device__ __forceinline__ void transpose_mat(const float* __restrict__ W, int K, int N, int Npad, bf16_t* __restrict__ WT, int blk_mul, int blk_off,
;                                               LAS float* scr, int gw, int NGW, int lane, const float* __restrict__ gk = nullptr) {
;     ...
;         const int kb = it / nblk, nb = it % nblk, k0 = 64 * kb, n0 = 32 * nb;
;         const int ncol = n0 + (lane & 31);
; #pragma unroll
;         for (int i = 0; i < 32; ++i) { const int kk = 2 * i + (lane >> 5); float w = (ncol < N) ? W[(size_t)(k0 + kk) * N + ncol] : 0.f; if (gk) w *= gk[k0 + kk]; scr[kk * 33 + (lane & 31)] = w; }
.LBB0_2527:
	v_mov_b32_e32 v155, 0
	s_and_saveexec_b64 s[20:21], s[4:5]
	s_cbranch_execz .LBB0_2529
	v_or_b32_e32 v36, s18, v63
	v_mad_i64_i32 v[36:37], s[30:31], v36, s70, v[34:35]
	global_load_dword v155, v[36:37], off
.LBB0_2529:
	s_or_b64 exec, exec, s[20:21]
	s_and_b64 vcc, exec, s[6:7]
	s_cbranch_vccnz .LBB0_2531
	s_ashr_i32 s19, s18, 31
	v_lshl_add_u64 v[102:103], s[18:19], 0, v[16:17]
	v_lshl_add_u64 v[102:103], v[102:103], 2, v[28:29]
	global_load_dword v187, v[102:103], off offset:152
.LBB0_2531:
	v_mov_b32_e32 v156, 0
	s_and_saveexec_b64 s[20:21], s[4:5]
	s_cbranch_execz .LBB0_2533
	v_or_b32_e32 v36, s18, v64
	v_mad_i64_i32 v[36:37], s[30:31], v36, s70, v[34:35]
	global_load_dword v156, v[36:37], off
.LBB0_2533:
	s_or_b64 exec, exec, s[20:21]
	s_and_b64 vcc, exec, s[6:7]
	s_cbranch_vccnz .LBB0_2535
	s_ashr_i32 s19, s18, 31
	v_lshl_add_u64 v[102:103], s[18:19], 0, v[16:17]
	v_lshl_add_u64 v[102:103], v[102:103], 2, v[28:29]
	global_load_dword v188, v[102:103], off offset:160
.LBB0_2535:
	v_mov_b32_e32 v157, 0
	s_and_saveexec_b64 s[20:21], s[4:5]
	s_cbranch_execz .LBB0_2537
	v_or_b32_e32 v36, s18, v66
	v_mad_i64_i32 v[36:37], s[30:31], v36, s70, v[34:35]
	global_load_dword v157, v[36:37], off
.LBB0_2537:
	s_or_b64 exec, exec, s[20:21]
	s_and_b64 vcc, exec, s[6:7]
	s_cbranch_vccnz .LBB0_2539
	s_ashr_i32 s19, s18, 31
	v_lshl_add_u64 v[102:103], s[18:19], 0, v[16:17]
	v_lshl_add_u64 v[102:103], v[102:103], 2, v[28:29]
	global_load_dword v189, v[102:103], off offset:168
.LBB0_2539:
	v_mov_b32_e32 v158, 0
	s_and_saveexec_b64 s[20:21], s[4:5]
	s_cbranch_execz .LBB0_2541
	v_or_b32_e32 v36, s18, v67
	v_mad_i64_i32 v[36:37], s[30:31], v36, s70, v[34:35]
	global_load_dword v158, v[36:37], off
.LBB0_2541:
	s_or_b64 exec, exec, s[20:21]
	s_and_b64 vcc, exec, s[6:7]
	s_cbranch_vccnz .LBB0_2543
	s_ashr_i32 s19, s18, 31
	v_lshl_add_u64 v[102:103], s[18:19], 0, v[16:17]
	v_lshl_add_u64 v[102:103], v[102:103], 2, v[28:29]
	global_load_dword v190, v[102:103], off offset:176
.LBB0_2543:
	v_mov_b32_e32 v159, 0
	s_and_saveexec_b64 s[20:21], s[4:5]
	s_cbranch_execz .LBB0_2545
	v_or_b32_e32 v36, s18, v68
	v_mad_i64_i32 v[36:37], s[30:31], v36, s70, v[34:35]
	global_load_dword v159, v[36:37], off
.LBB0_2545:
	s_or_b64 exec, exec, s[20:21]
	s_and_b64 vcc, exec, s[6:7]
	s_cbranch_vccnz .LBB0_2547
	s_ashr_i32 s19, s18, 31
	v_lshl_add_u64 v[102:103], s[18:19], 0, v[16:17]
	v_lshl_add_u64 v[102:103], v[102:103], 2, v[28:29]
	global_load_dword v191, v[102:103], off offset:184
.LBB0_2547:
	v_mov_b32_e32 v160, 0
	s_and_saveexec_b64 s[20:21], s[4:5]
	s_cbranch_execz .LBB0_2549
	v_or_b32_e32 v36, s18, v69
	v_mad_i64_i32 v[36:37], s[30:31], v36, s70, v[34:35]
	global_load_dword v160, v[36:37], off
.LBB0_2549:
	s_or_b64 exec, exec, s[20:21]
	s_and_b64 vcc, exec, s[6:7]
	s_cbranch_vccnz .LBB0_2551
	s_ashr_i32 s19, s18, 31
	v_lshl_add_u64 v[102:103], s[18:19], 0, v[16:17]
	v_lshl_add_u64 v[102:103], v[102:103], 2, v[28:29]
	global_load_dword v192, v[102:103], off offset:192
.LBB0_2551:
	v_mov_b32_e32 v161, 0
	s_and_saveexec_b64 s[20:21], s[4:5]
	s_cbranch_execz .LBB0_2553
	v_or_b32_e32 v36, s18, v71
	v_mad_i64_i32 v[36:37], s[30:31], v36, s70, v[34:35]
	global_load_dword v161, v[36:37], off
.LBB0_2553:
	s_or_b64 exec, exec, s[20:21]
	s_and_b64 vcc, exec, s[6:7]
	s_cbranch_vccnz .LBB0_2555
	s_ashr_i32 s19, s18, 31
	v_lshl_add_u64 v[102:103], s[18:19], 0, v[16:17]
	v_lshl_add_u64 v[102:103], v[102:103], 2, v[28:29]
	global_load_dword v193, v[102:103], off offset:200
.LBB0_2555:
	v_mov_b32_e32 v162, 0
	s_and_saveexec_b64 s[20:21], s[4:5]
	s_cbranch_execz .LBB0_2557
	v_or_b32_e32 v36, s18, v72
	v_mad_i64_i32 v[36:37], s[30:31], v36, s70, v[34:35]
	global_load_dword v162, v[36:37], off
.LBB0_2557:
	s_or_b64 exec, exec, s[20:21]
	s_and_b64 vcc, exec, s[6:7]
	s_cbranch_vccnz .LBB0_2559
	s_ashr_i32 s19, s18, 31
	v_lshl_add_u64 v[102:103], s[18:19], 0, v[16:17]
	v_lshl_add_u64 v[102:103], v[102:103], 2, v[28:29]
	global_load_dword v194, v[102:103], off offset:208
; #define LDS_WAIT() asm volatile("s_waitcnt lgkmcnt(0)" ::: "memory")
; __device__ __forceinline__ void transpose_mat(const float* __restrict__ W, int K, int N, int Npad, bf16_t* __restrict__ WT, int blk_mul, int blk_off,
;                                               LAS float* scr, int gw, int NGW, int lane, const float* __restrict__ gk = nullptr) {
;     ...
;         const int kb = it / nblk, nb = it % nblk, k0 = 64 * kb, n0 = 32 * nb;
;         const int ncol = n0 + (lane & 31);
; #pragma unroll
;         for (int i = 0; i < 32; ++i) { const int kk = 2 * i + (lane >> 5); float w = (ncol < N) ? W[(size_t)(k0 + kk) * N + ncol] : 0.f; if (gk) w *= gk[k0 + kk]; scr[kk * 33 + (lane & 31)] = w; }
;         LDS_WAIT();
.LBB0_2559:
	v_mov_b32_e32 v163, 0
	s_and_saveexec_b64 s[20:21], s[4:5]
	s_cbranch_execz .LBB0_2561
	v_or_b32_e32 v37, s18, v75
	v_mad_i64_i32 v[102:103], s[30:31], v37, s70, v[34:35]
	global_load_dword v163, v[102:103], off
.LBB0_2561:
	s_or_b64 exec, exec, s[20:21]
	s_and_b64 vcc, exec, s[6:7]
	s_cbranch_vccnz .LBB0_2563
	s_ashr_i32 s19, s18, 31
	v_lshl_add_u64 v[102:103], s[18:19], 0, v[16:17]
	v_lshl_add_u64 v[102:103], v[102:103], 2, v[28:29]
	global_load_dword v195, v[102:103], off offset:216
.LBB0_2563:
	v_mov_b32_e32 v164, 0
	s_and_saveexec_b64 s[20:21], s[4:5]
	s_cbranch_execz .LBB0_2565
	v_or_b32_e32 v37, s18, v76
	v_mad_i64_i32 v[102:103], s[30:31], v37, s70, v[34:35]
	global_load_dword v164, v[102:103], off
.LBB0_2565:
	s_or_b64 exec, exec, s[20:21]
	s_and_b64 vcc, exec, s[6:7]
	s_cbranch_vccnz .LBB0_2567
	s_ashr_i32 s19, s18, 31
	v_lshl_add_u64 v[102:103], s[18:19], 0, v[16:17]
	v_lshl_add_u64 v[102:103], v[102:103], 2, v[28:29]
	global_load_dword v196, v[102:103], off offset:224
.LBB0_2567:
	v_mov_b32_e32 v165, 0
	s_and_saveexec_b64 s[20:21], s[4:5]
	s_cbranch_execz .LBB0_2569
	v_or_b32_e32 v37, s18, v77
	v_mad_i64_i32 v[102:103], s[30:31], v37, s70, v[34:35]
	global_load_dword v165, v[102:103], off
.LBB0_2569:
	s_or_b64 exec, exec, s[20:21]
	s_and_b64 vcc, exec, s[6:7]
	s_cbranch_vccnz .LBB0_2571
	s_ashr_i32 s19, s18, 31
	v_lshl_add_u64 v[102:103], s[18:19], 0, v[16:17]
	v_lshl_add_u64 v[102:103], v[102:103], 2, v[28:29]
	global_load_dword v197, v[102:103], off offset:232
.LBB0_2571:
	v_mov_b32_e32 v166, 0
	s_and_saveexec_b64 s[20:21], s[4:5]
	s_cbranch_execz .LBB0_2573
	v_or_b32_e32 v37, s18, v78
	v_mad_i64_i32 v[102:103], s[30:31], v37, s70, v[34:35]
	global_load_dword v166, v[102:103], off
.LBB0_2573:
	s_or_b64 exec, exec, s[20:21]
	s_and_b64 vcc, exec, s[6:7]
	s_cbranch_vccnz .LBB0_2575
	s_ashr_i32 s19, s18, 31
	v_lshl_add_u64 v[102:103], s[18:19], 0, v[16:17]
	v_lshl_add_u64 v[102:103], v[102:103], 2, v[28:29]
	global_load_dword v198, v[102:103], off offset:240
.LBB0_2575:
	v_mov_b32_e32 v167, 0
	s_and_saveexec_b64 s[6:7], s[4:5]
	s_cbranch_execz .LBB0_2577
	v_or_b32_e32 v37, s18, v79
	v_mad_i64_i32 v[34:35], s[4:5], v37, s70, v[34:35]
	global_load_dword v167, v[34:35], off
.LBB0_2577:
	s_or_b64 exec, exec, s[6:7]
	s_and_b64 vcc, exec, s[2:3]
	s_cbranch_vccz .LBB0_2579
	s_ashr_i32 s19, s18, 31
	v_lshl_add_u64 v[34:35], s[18:19], 0, v[16:17]
	v_lshl_add_u64 v[34:35], v[34:35], 2, v[28:29]
	global_load_dword v199, v[34:35], off offset:248
.LBB0_2579:
.LBB0_2580:
	s_ashr_i32 s19, s18, 31
	v_mov_b32_e32 v34, v37
	s_waitcnt vmcnt(0)
	s_and_b64 vcc, exec, s[2:3]
	s_cbranch_vccz .Ltp3_nomul_2
	v_mul_f32_e32 v152, v152, v184
	v_mul_f32_e32 v153, v153, v185
	v_mul_f32_e32 v154, v154, v186
	v_mul_f32_e32 v155, v155, v187
	v_mul_f32_e32 v156, v156, v188
	v_mul_f32_e32 v157, v157, v189
	v_mul_f32_e32 v158, v158, v190
	v_mul_f32_e32 v159, v159, v191
	v_mul_f32_e32 v160, v160, v192
	v_mul_f32_e32 v161, v161, v193
	v_mul_f32_e32 v162, v162, v194
	v_mul_f32_e32 v163, v163, v195
	v_mul_f32_e32 v164, v164, v196
	v_mul_f32_e32 v165, v165, v197
	v_mul_f32_e32 v166, v166, v198
	v_mul_f32_e32 v167, v167, v199
.Ltp3_nomul_2:
	v_add_u32_e32 v37, v39, v60
	ds_write_b32 v37, v152
	v_add_u32_e32 v37, v39, v92
	ds_write_b32 v37, v153
	v_add_u32_e32 v37, v39, v93
	ds_write_b32 v37, v154
	v_add_u32_e32 v37, v39, v94
	ds_write_b32 v37, v155
	v_add_u32_e32 v37, v39, v65
	ds_write_b32 v37, v156
	v_add_u32_e32 v37, v39, v95
	ds_write_b32 v37, v157
	v_add_u32_e32 v37, v39, v96
	ds_write_b32 v37, v158
	v_add_u32_e32 v37, v39, v97
	ds_write_b32 v37, v159
	v_add_u32_e32 v37, v39, v70
	ds_write_b32 v37, v160
	v_add_u32_e32 v37, v39, v98
	ds_write_b32 v37, v161
	v_add_u32_e32 v36, v39, v73
	ds_write_b32 v36, v162
	ds_write_b32 v36, v163 offset:264
	ds_write_b32 v36, v164 offset:528
	ds_write_b32 v36, v165 offset:792
	ds_write_b32 v36, v166 offset:1056
	v_mov_b32_e32 v34, v167
	s_branch .LBB0_2450

; #define LAS __attribute__((address_space(3)))
; __device__ __forceinline__ void transpose_mat(const float* __restrict__ W, int K, int N, int Npad, bf16_t* __restrict__ WT, int blk_mul, int blk_off,
;                                               LAS float* scr, int gw, int NGW, int lane, const float* __restrict__ gk = nullptr) {
;     ...
;         const int kb = it / nblk, nb = it % nblk, k0 = 64 * kb, n0 = 32 * nb;
;         const int ncol = n0 + (lane & 31);
; #pragma unroll
;         for (int i = 0; i < 32; ++i) { const int kk = 2 * i + (lane >> 5); float w = (ncol < N) ? W[(size_t)(k0 + kk) * N + ncol] : 0.f; if (gk) w *= gk[k0 + kk]; scr[kk * 33 + (lane & 31)] = w; }
; __global__ void __launch_bounds__(NTHR, 2) hymba_fwd(KArgs a) {
;     ...
;             convert_layer(1, PIN(2), PIN(3), PIN(4), PIN(1), PIN(6), PIN(5), PIN(18), PIN(8), PIN(10), PIN(14), PIN(16), ws, (LAS float*)(lds + wave * 16384), (bid - cfirst) * 8 + wave, (G - cfirst) * 8, lane_);
.LBB0_2586:
	s_mul_hi_i32 s4, s26, 0x2e8ba2e9
	s_lshr_b32 s5, s4, 31
	s_ashr_i32 s27, s4, 4
	s_add_i32 s27, s27, s5
	s_mul_i32 s28, s27, 0xfffff500
	s_add_i32 s4, s28, s15
	v_add_u32_e32 v34, s4, v104
	s_lshl_b32 s16, s27, 6
	s_movk_i32 s4, 0xb00
	v_ashrrev_i32_e32 v35, 31, v34
	v_cmp_gt_i32_e64 s[4:5], s4, v34
	v_lshl_add_u64 v[34:35], v[34:35], 2, v[30:31]
	v_mov_b32_e32 v136, 0
	v_or_b32_e32 v36, s16, v16
	s_and_saveexec_b64 s[6:7], s[4:5]
	s_cbranch_execz .LBB0_2588
	v_mad_i64_i32 v[100:101], s[20:21], v36, s70, v[34:35]
	global_load_dword v136, v[100:101], off

; __device__ __forceinline__ void transpose_mat(const float* __restrict__ W, int K, int N, int Npad, bf16_t* __restrict__ WT, int blk_mul, int blk_off,
;                                               LAS float* scr, int gw, int NGW, int lane, const float* __restrict__ gk = nullptr) {
;     ...
;         const int kb = it / nblk, nb = it % nblk, k0 = 64 * kb, n0 = 32 * nb;
;         const int ncol = n0 + (lane & 31);
; #pragma unroll
;         for (int i = 0; i < 32; ++i) { const int kk = 2 * i + (lane >> 5); float w = (ncol < N) ? W[(size_t)(k0 + kk) * N + ncol] : 0.f; if (gk) w *= gk[k0 + kk]; scr[kk * 33 + (lane & 31)] = w; }
.LBB0_2590:
	v_mov_b32_e32 v137, 0
	s_and_saveexec_b64 s[20:21], s[4:5]
	s_cbranch_execz .LBB0_2592
	v_or_b32_e32 v37, s16, v41
	v_mad_i64_i32 v[100:101], s[30:31], v37, s70, v[34:35]
	global_load_dword v137, v[100:101], off
.LBB0_2592:
	s_or_b64 exec, exec, s[20:21]
	s_and_b64 vcc, exec, s[6:7]
	s_cbranch_vccnz .LBB0_2594
	s_ashr_i32 s17, s16, 31
	v_lshl_add_u64 v[100:101], s[16:17], 0, v[16:17]
	v_lshl_add_u64 v[100:101], v[100:101], 2, v[28:29]
	global_load_dword v169, v[100:101], off offset:8
.LBB0_2594:
	v_mov_b32_e32 v138, 0
	s_and_saveexec_b64 s[20:21], s[4:5]
	s_cbranch_execz .LBB0_2596
	v_or_b32_e32 v37, s16, v42
	v_mad_i64_i32 v[100:101], s[30:31], v37, s70, v[34:35]
	global_load_dword v138, v[100:101], off
.LBB0_2596:
	s_or_b64 exec, exec, s[20:21]
	s_and_b64 vcc, exec, s[6:7]
	s_cbranch_vccnz .LBB0_2598
	s_ashr_i32 s17, s16, 31
	v_lshl_add_u64 v[100:101], s[16:17], 0, v[16:17]
	v_lshl_add_u64 v[100:101], v[100:101], 2, v[28:29]
	global_load_dword v170, v[100:101], off offset:16
.LBB0_2598:
	v_mov_b32_e32 v139, 0
	s_and_saveexec_b64 s[20:21], s[4:5]
	s_cbranch_execz .LBB0_2600
	v_or_b32_e32 v37, s16, v43
	v_mad_i64_i32 v[100:101], s[30:31], v37, s70, v[34:35]
	global_load_dword v139, v[100:101], off
.LBB0_2600:
	s_or_b64 exec, exec, s[20:21]
	s_and_b64 vcc, exec, s[6:7]
	s_cbranch_vccnz .LBB0_2602
	s_ashr_i32 s17, s16, 31
	v_lshl_add_u64 v[100:101], s[16:17], 0, v[16:17]
	v_lshl_add_u64 v[100:101], v[100:101], 2, v[28:29]
	global_load_dword v171, v[100:101], off offset:24
.LBB0_2602:
	v_mov_b32_e32 v140, 0
	s_and_saveexec_b64 s[20:21], s[4:5]
	s_cbranch_execz .LBB0_2604
	v_or_b32_e32 v37, s16, v44
	v_mad_i64_i32 v[100:101], s[30:31], v37, s70, v[34:35]
	global_load_dword v140, v[100:101], off
.LBB0_2604:
	s_or_b64 exec, exec, s[20:21]
	s_and_b64 vcc, exec, s[6:7]
	s_cbranch_vccnz .LBB0_2606
	s_ashr_i32 s17, s16, 31
	v_lshl_add_u64 v[102:103], s[16:17], 0, v[16:17]
	v_lshl_add_u64 v[102:103], v[102:103], 2, v[28:29]
	global_load_dword v172, v[102:103], off offset:32
.LBB0_2606:
	v_mov_b32_e32 v141, 0
	s_and_saveexec_b64 s[20:21], s[4:5]
	s_cbranch_execz .LBB0_2608
	v_or_b32_e32 v100, s16, v46
	v_mad_i64_i32 v[100:101], s[30:31], v100, s70, v[34:35]
	global_load_dword v141, v[100:101], off
.LBB0_2608:
	s_or_b64 exec, exec, s[20:21]
	s_and_b64 vcc, exec, s[6:7]
	s_cbranch_vccnz .LBB0_2610
	s_ashr_i32 s17, s16, 31
	v_lshl_add_u64 v[102:103], s[16:17], 0, v[16:17]
	v_lshl_add_u64 v[102:103], v[102:103], 2, v[28:29]
	global_load_dword v173, v[102:103], off offset:40
.LBB0_2610:
	v_mov_b32_e32 v142, 0
	s_and_saveexec_b64 s[20:21], s[4:5]
	s_cbranch_execz .LBB0_2612
	v_or_b32_e32 v100, s16, v47
	v_mad_i64_i32 v[100:101], s[30:31], v100, s70, v[34:35]
	global_load_dword v142, v[100:101], off
.LBB0_2612:
	s_or_b64 exec, exec, s[20:21]
	s_and_b64 vcc, exec, s[6:7]
	s_cbranch_vccnz .LBB0_2614
	s_ashr_i32 s17, s16, 31
	v_lshl_add_u64 v[102:103], s[16:17], 0, v[16:17]
	v_lshl_add_u64 v[102:103], v[102:103], 2, v[28:29]
	global_load_dword v174, v[102:103], off offset:48
.LBB0_2614:
	v_mov_b32_e32 v143, 0
	s_and_saveexec_b64 s[20:21], s[4:5]
	s_cbranch_execz .LBB0_2616
	v_or_b32_e32 v100, s16, v48
	v_mad_i64_i32 v[100:101], s[30:31], v100, s70, v[34:35]
	global_load_dword v143, v[100:101], off
.LBB0_2616:
	s_or_b64 exec, exec, s[20:21]
	s_and_b64 vcc, exec, s[6:7]
	s_cbranch_vccnz .LBB0_2618
	s_ashr_i32 s17, s16, 31
	v_lshl_add_u64 v[102:103], s[16:17], 0, v[16:17]
	v_lshl_add_u64 v[102:103], v[102:103], 2, v[28:29]
	global_load_dword v175, v[102:103], off offset:56
.LBB0_2618:
	v_mov_b32_e32 v144, 0
	s_and_saveexec_b64 s[20:21], s[4:5]
	s_cbranch_execz .LBB0_2620
	v_or_b32_e32 v100, s16, v49
	v_mad_i64_i32 v[100:101], s[30:31], v100, s70, v[34:35]
	global_load_dword v144, v[100:101], off
; __device__ __forceinline__ void transpose_mat(const float* __restrict__ W, int K, int N, int Npad, bf16_t* __restrict__ WT, int blk_mul, int blk_off,
;                                               LAS float* scr, int gw, int NGW, int lane, const float* __restrict__ gk = nullptr) {
;     ...
;         const int kb = it / nblk, nb = it % nblk, k0 = 64 * kb, n0 = 32 * nb;
;         const int ncol = n0 + (lane & 31);
; #pragma unroll
;         for (int i = 0; i < 32; ++i) { const int kk = 2 * i + (lane >> 5); float w = (ncol < N) ? W[(size_t)(k0 + kk) * N + ncol] : 0.f; if (gk) w *= gk[k0 + kk]; scr[kk * 33 + (lane & 31)] = w; }
.LBB0_2620:
	s_or_b64 exec, exec, s[20:21]
	s_and_b64 vcc, exec, s[6:7]
	s_cbranch_vccnz .LBB0_2622
	s_ashr_i32 s17, s16, 31
	v_lshl_add_u64 v[102:103], s[16:17], 0, v[16:17]
	v_lshl_add_u64 v[102:103], v[102:103], 2, v[28:29]
	global_load_dword v176, v[102:103], off offset:64
.LBB0_2622:
	v_mov_b32_e32 v145, 0
	s_and_saveexec_b64 s[20:21], s[4:5]
	s_cbranch_execz .LBB0_2624
	v_or_b32_e32 v101, s16, v51
	v_mad_i64_i32 v[102:103], s[30:31], v101, s70, v[34:35]
	global_load_dword v145, v[102:103], off
.LBB0_2624:
	s_or_b64 exec, exec, s[20:21]
	s_and_b64 vcc, exec, s[6:7]
	s_cbranch_vccnz .LBB0_2626
	s_ashr_i32 s17, s16, 31
	v_lshl_add_u64 v[102:103], s[16:17], 0, v[16:17]
	v_lshl_add_u64 v[102:103], v[102:103], 2, v[28:29]
	global_load_dword v177, v[102:103], off offset:72
.LBB0_2626:
	v_mov_b32_e32 v146, 0
	s_and_saveexec_b64 s[20:21], s[4:5]
	s_cbranch_execz .LBB0_2628
	v_or_b32_e32 v101, s16, v52
	v_mad_i64_i32 v[102:103], s[30:31], v101, s70, v[34:35]
	global_load_dword v146, v[102:103], off
.LBB0_2628:
	s_or_b64 exec, exec, s[20:21]
	s_and_b64 vcc, exec, s[6:7]
	s_cbranch_vccnz .LBB0_2630
	s_ashr_i32 s17, s16, 31
	v_lshl_add_u64 v[102:103], s[16:17], 0, v[16:17]
	v_lshl_add_u64 v[102:103], v[102:103], 2, v[28:29]
	global_load_dword v178, v[102:103], off offset:80
.LBB0_2630:
	v_mov_b32_e32 v147, 0
	s_and_saveexec_b64 s[20:21], s[4:5]
	s_cbranch_execz .LBB0_2632
	v_or_b32_e32 v101, s16, v53
	v_mad_i64_i32 v[102:103], s[30:31], v101, s70, v[34:35]
	global_load_dword v147, v[102:103], off
.LBB0_2632:
	s_or_b64 exec, exec, s[20:21]
	s_and_b64 vcc, exec, s[6:7]
	s_cbranch_vccnz .LBB0_2634
	s_ashr_i32 s17, s16, 31
	v_lshl_add_u64 v[102:103], s[16:17], 0, v[16:17]
	v_lshl_add_u64 v[102:103], v[102:103], 2, v[28:29]
	global_load_dword v179, v[102:103], off offset:88
.LBB0_2634:
	v_mov_b32_e32 v148, 0
	s_and_saveexec_b64 s[20:21], s[4:5]
	s_cbranch_execz .LBB0_2636
	v_or_b32_e32 v101, s16, v54
	v_mad_i64_i32 v[102:103], s[30:31], v101, s70, v[34:35]
	global_load_dword v148, v[102:103], off
.LBB0_2636:
	s_or_b64 exec, exec, s[20:21]
	s_and_b64 vcc, exec, s[6:7]
	s_cbranch_vccnz .LBB0_2638
	s_ashr_i32 s17, s16, 31
	v_lshl_add_u64 v[106:107], s[16:17], 0, v[16:17]
	v_lshl_add_u64 v[106:107], v[106:107], 2, v[28:29]
	global_load_dword v180, v[106:107], off offset:96
.LBB0_2638:
	v_mov_b32_e32 v149, 0
	s_and_saveexec_b64 s[20:21], s[4:5]
	s_cbranch_execz .LBB0_2640
	v_or_b32_e32 v102, s16, v56
	v_mad_i64_i32 v[102:103], s[30:31], v102, s70, v[34:35]
	global_load_dword v149, v[102:103], off
.LBB0_2640:
	s_or_b64 exec, exec, s[20:21]
	s_and_b64 vcc, exec, s[6:7]
	s_cbranch_vccnz .LBB0_2642
	s_ashr_i32 s17, s16, 31
	v_lshl_add_u64 v[106:107], s[16:17], 0, v[16:17]
	v_lshl_add_u64 v[106:107], v[106:107], 2, v[28:29]
	global_load_dword v181, v[106:107], off offset:104
.LBB0_2642:
	v_mov_b32_e32 v150, 0
	s_and_saveexec_b64 s[20:21], s[4:5]
	s_cbranch_execz .LBB0_2644
	v_or_b32_e32 v102, s16, v57
	v_mad_i64_i32 v[102:103], s[30:31], v102, s70, v[34:35]
	global_load_dword v150, v[102:103], off
.LBB0_2644:
	s_or_b64 exec, exec, s[20:21]
	s_and_b64 vcc, exec, s[6:7]
	s_cbranch_vccnz .LBB0_2646
	s_ashr_i32 s17, s16, 31
	v_lshl_add_u64 v[106:107], s[16:17], 0, v[16:17]
	v_lshl_add_u64 v[106:107], v[106:107], 2, v[28:29]
	global_load_dword v182, v[106:107], off offset:112
.LBB0_2646:
	v_mov_b32_e32 v151, 0
	s_and_saveexec_b64 s[20:21], s[4:5]
	s_cbranch_execz .LBB0_2648
	v_or_b32_e32 v102, s16, v58
	v_mad_i64_i32 v[102:103], s[30:31], v102, s70, v[34:35]
	global_load_dword v151, v[102:103], off
.LBB0_2648:
	s_or_b64 exec, exec, s[20:21]
	s_and_b64 vcc, exec, s[6:7]
	s_cbranch_vccnz .LBB0_2650
	s_ashr_i32 s17, s16, 31
	v_lshl_add_u64 v[106:107], s[16:17], 0, v[16:17]
	v_lshl_add_u64 v[106:107], v[106:107], 2, v[28:29]
	global_load_dword v183, v[106:107], off offset:120

; #define LDS_WAIT() asm volatile("s_waitcnt lgkmcnt(0)" ::: "memory")
; __device__ __forceinline__ void transpose_mat(const float* __restrict__ W, int K, int N, int Npad, bf16_t* __restrict__ WT, int blk_mul, int blk_off,
;                                               LAS float* scr, int gw, int NGW, int lane, const float* __restrict__ gk = nullptr) {
;     ...
;         const int kb = it / nblk, nb = it % nblk, k0 = 64 * kb, n0 = 32 * nb;
;         const int ncol = n0 + (lane & 31);
; #pragma unroll
;         for (int i = 0; i < 32; ++i) { const int kk = 2 * i + (lane >> 5); float w = (ncol < N) ? W[(size_t)(k0 + kk) * N + ncol] : 0.f; if (gk) w *= gk[k0 + kk]; scr[kk * 33 + (lane & 31)] = w; }
;         LDS_WAIT();
.Ltp4_nomul_1:
	v_add_u32_e32 v36, v39, v40
	ds_write_b32 v36, v136
	v_add_u32_e32 v100, v39, v80
	ds_write_b32 v100, v137
	v_add_u32_e32 v100, v39, v81
	ds_write_b32 v100, v138
	v_add_u32_e32 v100, v39, v82
	ds_write_b32 v100, v139
	v_add_u32_e32 v37, v39, v45
	ds_write_b32 v37, v140
	v_add_u32_e32 v101, v39, v83
	ds_write_b32 v101, v141
	v_add_u32_e32 v101, v39, v84
	ds_write_b32 v101, v142
	v_add_u32_e32 v101, v39, v85
	ds_write_b32 v101, v143
	v_add_u32_e32 v100, v39, v50
	ds_write_b32 v100, v144
	v_add_u32_e32 v102, v39, v86
	ds_write_b32 v102, v145
	v_add_u32_e32 v102, v39, v87
	ds_write_b32 v102, v146
	v_add_u32_e32 v102, v39, v88
	ds_write_b32 v102, v147
	v_add_u32_e32 v101, v39, v55
	ds_write_b32 v101, v148
	v_add_u32_e32 v103, v39, v89
	ds_write_b32 v103, v149
	v_add_u32_e32 v103, v39, v90
	ds_write_b32 v103, v150
	v_add_u32_e32 v103, v39, v91
	ds_write_b32 v103, v151
	v_mov_b32_e32 v152, 0
	s_and_saveexec_b64 s[20:21], s[4:5]
	s_cbranch_execz .LBB0_2652
	v_or_b32_e32 v102, s16, v59
	v_mad_i64_i32 v[102:103], s[30:31], v102, s70, v[34:35]
	global_load_dword v152, v[102:103], off
.LBB0_2652:
	s_or_b64 exec, exec, s[20:21]
	s_and_b64 vcc, exec, s[6:7]
	s_cbranch_vccnz .LBB0_2654
	s_ashr_i32 s17, s16, 31
	v_lshl_add_u64 v[106:107], s[16:17], 0, v[16:17]
	v_lshl_add_u64 v[106:107], v[106:107], 2, v[28:29]
	global_load_dword v184, v[106:107], off offset:128
.LBB0_2654:
	v_mov_b32_e32 v153, 0
	s_and_saveexec_b64 s[20:21], s[4:5]
	s_cbranch_execz .LBB0_2656
	v_or_b32_e32 v103, s16, v61
	v_mad_i64_i32 v[106:107], s[30:31], v103, s70, v[34:35]
	global_load_dword v153, v[106:107], off
.LBB0_2656:
	s_or_b64 exec, exec, s[20:21]
	s_and_b64 vcc, exec, s[6:7]
	s_cbranch_vccnz .LBB0_2658
	s_ashr_i32 s17, s16, 31
	v_lshl_add_u64 v[106:107], s[16:17], 0, v[16:17]
	v_lshl_add_u64 v[106:107], v[106:107], 2, v[28:29]
	global_load_dword v185, v[106:107], off offset:136
.LBB0_2658:
	v_mov_b32_e32 v154, 0
	s_and_saveexec_b64 s[20:21], s[4:5]
	s_cbranch_execz .LBB0_2660
	v_or_b32_e32 v103, s16, v62
	v_mad_i64_i32 v[106:107], s[30:31], v103, s70, v[34:35]
	global_load_dword v154, v[106:107], off
.LBB0_2660:
	s_or_b64 exec, exec, s[20:21]
	s_and_b64 vcc, exec, s[6:7]
	s_cbranch_vccnz .LBB0_2662
	s_ashr_i32 s17, s16, 31
	v_lshl_add_u64 v[106:107], s[16:17], 0, v[16:17]
	v_lshl_add_u64 v[106:107], v[106:107], 2, v[28:29]
	global_load_dword v186, v[106:107], off offset:144
.LBB0_2662:
	v_mov_b32_e32 v155, 0
	s_and_saveexec_b64 s[20:21], s[4:5]
	s_cbranch_execz .LBB0_2664
	v_or_b32_e32 v103, s16, v63
	v_mad_i64_i32 v[106:107], s[30:31], v103, s70, v[34:35]
	global_load_dword v155, v[106:107], off
.LBB0_2664:
	s_or_b64 exec, exec, s[20:21]
	s_and_b64 vcc, exec, s[6:7]
	s_cbranch_vccnz .LBB0_2666
	s_ashr_i32 s17, s16, 31
	v_lshl_add_u64 v[106:107], s[16:17], 0, v[16:17]
	v_lshl_add_u64 v[106:107], v[106:107], 2, v[28:29]
	global_load_dword v187, v[106:107], off offset:152
.LBB0_2666:
	v_mov_b32_e32 v156, 0
	s_and_saveexec_b64 s[20:21], s[4:5]
	s_cbranch_execz .LBB0_2668
	v_or_b32_e32 v103, s16, v64
	v_mad_i64_i32 v[106:107], s[30:31], v103, s70, v[34:35]
	global_load_dword v156, v[106:107], off
.LBB0_2668:
	s_or_b64 exec, exec, s[20:21]
	s_and_b64 vcc, exec, s[6:7]
	s_cbranch_vccnz .LBB0_2670
	s_ashr_i32 s17, s16, 31
	v_lshl_add_u64 v[108:109], s[16:17], 0, v[16:17]
	v_lshl_add_u64 v[108:109], v[108:109], 2, v[28:29]
	global_load_dword v188, v[108:109], off offset:160
.LBB0_2670:
	v_mov_b32_e32 v157, 0
	s_and_saveexec_b64 s[20:21], s[4:5]
	s_cbranch_execz .LBB0_2672
	v_or_b32_e32 v106, s16, v66
	v_mad_i64_i32 v[106:107], s[30:31], v106, s70, v[34:35]
	global_load_dword v157, v[106:107], off
.LBB0_2672:
	s_or_b64 exec, exec, s[20:21]
	s_and_b64 vcc, exec, s[6:7]
	s_cbranch_vccnz .LBB0_2674
	s_ashr_i32 s17, s16, 31
	v_lshl_add_u64 v[108:109], s[16:17], 0, v[16:17]
	v_lshl_add_u64 v[108:109], v[108:109], 2, v[28:29]
	global_load_dword v189, v[108:109], off offset:168
.LBB0_2674:
	v_mov_b32_e32 v158, 0
	s_and_saveexec_b64 s[20:21], s[4:5]
	s_cbranch_execz .LBB0_2676
	v_or_b32_e32 v106, s16, v67
	v_mad_i64_i32 v[106:107], s[30:31], v106, s70, v[34:35]
	global_load_dword v158, v[106:107], off
.LBB0_2676:
	s_or_b64 exec, exec, s[20:21]
	s_and_b64 vcc, exec, s[6:7]
	s_cbranch_vccnz .LBB0_2678
	s_ashr_i32 s17, s16, 31
	v_lshl_add_u64 v[108:109], s[16:17], 0, v[16:17]
	v_lshl_add_u64 v[108:109], v[108:109], 2, v[28:29]
	global_load_dword v190, v[108:109], off offset:176
.LBB0_2678:
	v_mov_b32_e32 v159, 0
	s_and_saveexec_b64 s[20:21], s[4:5]
	s_cbranch_execz .LBB0_2680
	v_or_b32_e32 v106, s16, v68
	v_mad_i64_i32 v[106:107], s[30:31], v106, s70, v[34:35]
	global_load_dword v159, v[106:107], off
.LBB0_2680:
	s_or_b64 exec, exec, s[20:21]
	s_and_b64 vcc, exec, s[6:7]
	s_cbranch_vccnz .LBB0_2682
	s_ashr_i32 s17, s16, 31
	v_lshl_add_u64 v[108:109], s[16:17], 0, v[16:17]
	v_lshl_add_u64 v[108:109], v[108:109], 2, v[28:29]
	global_load_dword v191, v[108:109], off offset:184
.LBB0_2682:
	v_mov_b32_e32 v160, 0
	s_and_saveexec_b64 s[20:21], s[4:5]
	s_cbranch_execz .LBB0_2684
	v_or_b32_e32 v106, s16, v69
	v_mad_i64_i32 v[106:107], s[30:31], v106, s70, v[34:35]
	global_load_dword v160, v[106:107], off
; #define LDS_WAIT() asm volatile("s_waitcnt lgkmcnt(0)" ::: "memory")
; __device__ __forceinline__ void transpose_mat(const float* __restrict__ W, int K, int N, int Npad, bf16_t* __restrict__ WT, int blk_mul, int blk_off,
;                                               LAS float* scr, int gw, int NGW, int lane, const float* __restrict__ gk = nullptr) {
;     ...
;         const int ncol = n0 + (lane & 31);
; #pragma unroll
;         for (int i = 0; i < 32; ++i) { const int kk = 2 * i + (lane >> 5); float w = (ncol < N) ? W[(size_t)(k0 + kk) * N + ncol] : 0.f; if (gk) w *= gk[k0 + kk]; scr[kk * 33 + (lane & 31)] = w; }
;         LDS_WAIT();
.LBB0_2684:
	s_or_b64 exec, exec, s[20:21]
	s_and_b64 vcc, exec, s[6:7]
	s_cbranch_vccnz .LBB0_2686
	s_ashr_i32 s17, s16, 31
	v_lshl_add_u64 v[108:109], s[16:17], 0, v[16:17]
	v_lshl_add_u64 v[108:109], v[108:109], 2, v[28:29]
	global_load_dword v192, v[108:109], off offset:192
.LBB0_2686:
	v_mov_b32_e32 v161, 0
	s_and_saveexec_b64 s[20:21], s[4:5]
	s_cbranch_execz .LBB0_2688
	v_or_b32_e32 v107, s16, v71
	v_mad_i64_i32 v[108:109], s[30:31], v107, s70, v[34:35]
	global_load_dword v161, v[108:109], off
.LBB0_2688:
	s_or_b64 exec, exec, s[20:21]
	s_and_b64 vcc, exec, s[6:7]
	s_cbranch_vccnz .LBB0_2690
	s_ashr_i32 s17, s16, 31
	v_lshl_add_u64 v[108:109], s[16:17], 0, v[16:17]
	v_lshl_add_u64 v[108:109], v[108:109], 2, v[28:29]
	global_load_dword v193, v[108:109], off offset:200
.LBB0_2690:
	v_mov_b32_e32 v162, 0
	s_and_saveexec_b64 s[20:21], s[4:5]
	s_cbranch_execz .LBB0_2692
	v_or_b32_e32 v107, s16, v72
	v_mad_i64_i32 v[108:109], s[30:31], v107, s70, v[34:35]
	global_load_dword v162, v[108:109], off
.LBB0_2692:
	s_or_b64 exec, exec, s[20:21]
	s_and_b64 vcc, exec, s[6:7]
	s_cbranch_vccnz .LBB0_2694
	s_ashr_i32 s17, s16, 31
	v_lshl_add_u64 v[110:111], s[16:17], 0, v[16:17]
	v_lshl_add_u64 v[110:111], v[110:111], 2, v[28:29]
	global_load_dword v194, v[110:111], off offset:208
.LBB0_2694:
	v_mov_b32_e32 v163, 0
	s_and_saveexec_b64 s[20:21], s[4:5]
	s_cbranch_execz .LBB0_2696
	v_or_b32_e32 v108, s16, v75
	v_mad_i64_i32 v[108:109], s[30:31], v108, s70, v[34:35]
	global_load_dword v163, v[108:109], off
.LBB0_2696:
	s_or_b64 exec, exec, s[20:21]
	s_and_b64 vcc, exec, s[6:7]
	s_cbranch_vccnz .LBB0_2698
	s_ashr_i32 s17, s16, 31
	v_lshl_add_u64 v[110:111], s[16:17], 0, v[16:17]
	v_lshl_add_u64 v[110:111], v[110:111], 2, v[28:29]
	global_load_dword v195, v[110:111], off offset:216
.LBB0_2698:
	v_mov_b32_e32 v164, 0
	s_and_saveexec_b64 s[20:21], s[4:5]
	s_cbranch_execz .LBB0_2700
	v_or_b32_e32 v108, s16, v76
	v_mad_i64_i32 v[108:109], s[30:31], v108, s70, v[34:35]
	global_load_dword v164, v[108:109], off
.LBB0_2700:
	s_or_b64 exec, exec, s[20:21]
	s_and_b64 vcc, exec, s[6:7]
	s_cbranch_vccnz .LBB0_2702
	s_ashr_i32 s17, s16, 31
	v_lshl_add_u64 v[110:111], s[16:17], 0, v[16:17]
	v_lshl_add_u64 v[110:111], v[110:111], 2, v[28:29]
	global_load_dword v196, v[110:111], off offset:224
.LBB0_2702:
	v_mov_b32_e32 v165, 0
	s_and_saveexec_b64 s[20:21], s[4:5]
	s_cbranch_execz .LBB0_2704
	v_or_b32_e32 v108, s16, v77
	v_mad_i64_i32 v[108:109], s[30:31], v108, s70, v[34:35]
	global_load_dword v165, v[108:109], off
.LBB0_2704:
	s_or_b64 exec, exec, s[20:21]
	s_and_b64 vcc, exec, s[6:7]
	s_cbranch_vccnz .LBB0_2706
	s_ashr_i32 s17, s16, 31
	v_lshl_add_u64 v[110:111], s[16:17], 0, v[16:17]
	v_lshl_add_u64 v[110:111], v[110:111], 2, v[28:29]
	global_load_dword v197, v[110:111], off offset:232
.LBB0_2706:
	v_mov_b32_e32 v166, 0
	s_and_saveexec_b64 s[20:21], s[4:5]
	s_cbranch_execz .LBB0_2708
	v_or_b32_e32 v108, s16, v78
	v_mad_i64_i32 v[108:109], s[30:31], v108, s70, v[34:35]
	global_load_dword v166, v[108:109], off
.LBB0_2708:
	s_or_b64 exec, exec, s[20:21]
	s_and_b64 vcc, exec, s[6:7]
	s_cbranch_vccnz .LBB0_2710
	s_ashr_i32 s17, s16, 31
	v_lshl_add_u64 v[110:111], s[16:17], 0, v[16:17]
	v_lshl_add_u64 v[110:111], v[110:111], 2, v[28:29]
	global_load_dword v198, v[110:111], off offset:240
.LBB0_2710:
	v_mov_b32_e32 v167, 0
	s_and_saveexec_b64 s[6:7], s[4:5]
	s_cbranch_execz .LBB0_2712
	v_or_b32_e32 v108, s16, v79
	v_mad_i64_i32 v[34:35], s[4:5], v108, s70, v[34:35]
	global_load_dword v167, v[34:35], off
.LBB0_2712:
	s_or_b64 exec, exec, s[6:7]
	s_and_b64 vcc, exec, s[2:3]
	s_cbranch_vccz .LBB0_2714
	s_ashr_i32 s17, s16, 31
	v_lshl_add_u64 v[34:35], s[16:17], 0, v[16:17]
	v_lshl_add_u64 v[34:35], v[34:35], 2, v[28:29]
	global_load_dword v199, v[34:35], off offset:248
.LBB0_2714:
.LBB0_2715:
	s_ashr_i32 s17, s16, 31
	v_mov_b32_e32 v34, v108
	s_waitcnt vmcnt(0)
	s_and_b64 vcc, exec, s[2:3]
	s_cbranch_vccz .Ltp4_nomul_2
	v_mul_f32_e32 v152, v152, v184
	v_mul_f32_e32 v153, v153, v185
	v_mul_f32_e32 v154, v154, v186
	v_mul_f32_e32 v155, v155, v187
	v_mul_f32_e32 v156, v156, v188
	v_mul_f32_e32 v157, v157, v189
	v_mul_f32_e32 v158, v158, v190
	v_mul_f32_e32 v159, v159, v191
	v_mul_f32_e32 v160, v160, v192
	v_mul_f32_e32 v161, v161, v193
	v_mul_f32_e32 v162, v162, v194
	v_mul_f32_e32 v163, v163, v195
	v_mul_f32_e32 v164, v164, v196
	v_mul_f32_e32 v165, v165, v197
	v_mul_f32_e32 v166, v166, v198
	v_mul_f32_e32 v167, v167, v199
.Ltp4_nomul_2:
	v_add_u32_e32 v102, v39, v60
	ds_write_b32 v102, v152
	v_add_u32_e32 v106, v39, v92
	ds_write_b32 v106, v153
	v_add_u32_e32 v106, v39, v93
	ds_write_b32 v106, v154
	v_add_u32_e32 v106, v39, v94
	ds_write_b32 v106, v155
	v_add_u32_e32 v103, v39, v65
	ds_write_b32 v103, v156
	v_add_u32_e32 v107, v39, v95
	ds_write_b32 v107, v157
	v_add_u32_e32 v107, v39, v96
	ds_write_b32 v107, v158
	v_add_u32_e32 v107, v39, v97
	ds_write_b32 v107, v159
	v_add_u32_e32 v106, v39, v70
	ds_write_b32 v106, v160
	v_add_u32_e32 v108, v39, v98
	ds_write_b32 v108, v161
	v_add_u32_e32 v107, v39, v73
	ds_write_b32 v107, v162
	ds_write_b32 v107, v163 offset:264
	ds_write_b32 v107, v164 offset:528
	ds_write_b32 v107, v165 offset:792
	ds_write_b32 v107, v166 offset:1056
	v_mov_b32_e32 v34, v167
	s_branch .LBB0_2585

; #define LDS_WAIT() asm volatile("s_waitcnt lgkmcnt(0)" ::: "memory")
; __device__ __forceinline__ void transpose_mat(const float* __restrict__ W, int K, int N, int Npad, bf16_t* __restrict__ WT, int blk_mul, int blk_off,
;                                               LAS float* scr, int gw, int NGW, int lane, const float* __restrict__ gk = nullptr) {
;     ...
;         const int ncol = n0 + (lane & 31);
; #pragma unroll
;         for (int i = 0; i < 32; ++i) { const int kk = 2 * i + (lane >> 5); float w = (ncol < N) ? W[(size_t)(k0 + kk) * N + ncol] : 0.f; if (gk) w *= gk[k0 + kk]; scr[kk * 33 + (lane & 31)] = w; }
;         LDS_WAIT();
.LBB0_2737:
	s_mul_hi_i32 s4, s14, 0x66666667
	s_lshr_b32 s5, s4, 31
	s_ashr_i32 s4, s4, 5
	s_add_i32 s4, s4, s5
	s_mul_i32 s15, s4, 0xfffff600
	s_add_i32 s15, s15, s12
	v_add_u32_e32 v6, s15, v25
	s_lshl_b32 s8, s4, 6
	s_movk_i32 s4, 0x9b8
	v_ashrrev_i32_e32 v7, 31, v6
	v_cmp_gt_i32_e64 s[4:5], s4, v6
	v_lshl_add_u64 v[6:7], v[6:7], 2, v[0:1]
	v_mov_b32_e32 v136, 0
	v_or_b32_e32 v8, s8, v16
	s_and_saveexec_b64 s[6:7], s[4:5]
	s_cbranch_execz .LBB0_2739
	s_movk_i32 s9, 0x26e0
	v_mad_i64_i32 v[10:11], s[10:11], v8, s9, v[6:7]
	global_load_dword v136, v[10:11], off
.LBB0_2739:
	s_or_b64 exec, exec, s[6:7]
	v_cndmask_b32_e64 v9, 0, 1, s[2:3]
	v_cmp_ne_u32_e64 s[6:7], 1, v9
	s_andn2_b64 vcc, exec, s[2:3]
	s_cbranch_vccnz .LBB0_2741
	v_ashrrev_i32_e32 v9, 31, v8
	v_lshl_add_u64 v[8:9], v[8:9], 2, v[2:3]
	global_load_dword v168, v[8:9], off
.LBB0_2741:
	v_mov_b32_e32 v137, 0
	v_or_b32_e32 v8, s8, v41
	s_and_saveexec_b64 s[10:11], s[4:5]
	s_cbranch_execz .LBB0_2743
	s_movk_i32 s9, 0x26e0
	v_mad_i64_i32 v[10:11], s[16:17], v8, s9, v[6:7]
	global_load_dword v137, v[10:11], off
.LBB0_2743:
	s_or_b64 exec, exec, s[10:11]
	s_and_b64 vcc, exec, s[6:7]
	s_cbranch_vccnz .LBB0_2745
	v_ashrrev_i32_e32 v9, 31, v8
	v_lshl_add_u64 v[8:9], v[8:9], 2, v[2:3]
	global_load_dword v169, v[8:9], off
.LBB0_2745:
	v_mov_b32_e32 v138, 0
	v_or_b32_e32 v8, s8, v42
	s_and_saveexec_b64 s[10:11], s[4:5]
	s_cbranch_execz .LBB0_2747
	s_movk_i32 s9, 0x26e0
	v_mad_i64_i32 v[10:11], s[16:17], v8, s9, v[6:7]
	global_load_dword v138, v[10:11], off
.LBB0_2747:
	s_or_b64 exec, exec, s[10:11]
	s_and_b64 vcc, exec, s[6:7]
	s_cbranch_vccnz .LBB0_2749
	v_ashrrev_i32_e32 v9, 31, v8
	v_lshl_add_u64 v[8:9], v[8:9], 2, v[2:3]
	global_load_dword v170, v[8:9], off
.LBB0_2749:
	v_mov_b32_e32 v139, 0
	v_or_b32_e32 v8, s8, v43
	s_and_saveexec_b64 s[10:11], s[4:5]
	s_cbranch_execz .LBB0_2751
	s_movk_i32 s9, 0x26e0
	v_mad_i64_i32 v[10:11], s[16:17], v8, s9, v[6:7]
	global_load_dword v139, v[10:11], off
.LBB0_2751:
	s_or_b64 exec, exec, s[10:11]
	s_and_b64 vcc, exec, s[6:7]
	s_cbranch_vccnz .LBB0_2753
	v_ashrrev_i32_e32 v9, 31, v8
	v_lshl_add_u64 v[8:9], v[8:9], 2, v[2:3]
	global_load_dword v171, v[8:9], off
.LBB0_2753:
	v_mov_b32_e32 v140, 0
	v_or_b32_e32 v8, s8, v44
	s_and_saveexec_b64 s[10:11], s[4:5]
	s_cbranch_execz .LBB0_2755
	s_movk_i32 s9, 0x26e0
	v_mad_i64_i32 v[10:11], s[16:17], v8, s9, v[6:7]
	global_load_dword v140, v[10:11], off
.LBB0_2755:
	s_or_b64 exec, exec, s[10:11]
	s_and_b64 vcc, exec, s[6:7]
	s_cbranch_vccnz .LBB0_2757
	v_ashrrev_i32_e32 v9, 31, v8
	v_lshl_add_u64 v[8:9], v[8:9], 2, v[2:3]
	global_load_dword v172, v[8:9], off
.LBB0_2757:
	v_mov_b32_e32 v141, 0
	v_or_b32_e32 v8, s8, v46
	s_and_saveexec_b64 s[10:11], s[4:5]
	s_cbranch_execz .LBB0_2759
	s_movk_i32 s9, 0x26e0
	v_mad_i64_i32 v[10:11], s[16:17], v8, s9, v[6:7]
	global_load_dword v141, v[10:11], off
.LBB0_2759:
	s_or_b64 exec, exec, s[10:11]
	s_and_b64 vcc, exec, s[6:7]
	s_cbranch_vccnz .LBB0_2761
	v_ashrrev_i32_e32 v9, 31, v8
	v_lshl_add_u64 v[8:9], v[8:9], 2, v[2:3]
	global_load_dword v173, v[8:9], off
.LBB0_2761:
	v_mov_b32_e32 v142, 0
	v_or_b32_e32 v8, s8, v47
	s_and_saveexec_b64 s[10:11], s[4:5]
	s_cbranch_execz .LBB0_2763
	s_movk_i32 s9, 0x26e0
	v_mad_i64_i32 v[10:11], s[16:17], v8, s9, v[6:7]
	global_load_dword v142, v[10:11], off
.LBB0_2763:
	s_or_b64 exec, exec, s[10:11]
	s_and_b64 vcc, exec, s[6:7]
	s_cbranch_vccnz .LBB0_2765
	v_ashrrev_i32_e32 v9, 31, v8
	v_lshl_add_u64 v[8:9], v[8:9], 2, v[2:3]
	global_load_dword v174, v[8:9], off
.LBB0_2765:
	v_mov_b32_e32 v143, 0
	v_or_b32_e32 v8, s8, v48
	s_and_saveexec_b64 s[10:11], s[4:5]
	s_cbranch_execz .LBB0_2767
	s_movk_i32 s9, 0x26e0
	v_mad_i64_i32 v[10:11], s[16:17], v8, s9, v[6:7]
	global_load_dword v143, v[10:11], off
; #define LDS_WAIT() asm volatile("s_waitcnt lgkmcnt(0)" ::: "memory")
; __device__ __forceinline__ void transpose_mat(const float* __restrict__ W, int K, int N, int Npad, bf16_t* __restrict__ WT, int blk_mul, int blk_off,
;                                               LAS float* scr, int gw, int NGW, int lane, const float* __restrict__ gk = nullptr) {
;     ...
;         const int ncol = n0 + (lane & 31);
; #pragma unroll
;         for (int i = 0; i < 32; ++i) { const int kk = 2 * i + (lane >> 5); float w = (ncol < N) ? W[(size_t)(k0 + kk) * N + ncol] : 0.f; if (gk) w *= gk[k0 + kk]; scr[kk * 33 + (lane & 31)] = w; }
;         LDS_WAIT();
.LBB0_2767:
	s_or_b64 exec, exec, s[10:11]
	s_and_b64 vcc, exec, s[6:7]
	s_cbranch_vccnz .LBB0_2769
	v_ashrrev_i32_e32 v9, 31, v8
	v_lshl_add_u64 v[8:9], v[8:9], 2, v[2:3]
	global_load_dword v175, v[8:9], off
.LBB0_2769:
	v_mov_b32_e32 v144, 0
	v_or_b32_e32 v8, s8, v49
	s_and_saveexec_b64 s[10:11], s[4:5]
	s_cbranch_execz .LBB0_2771
	s_movk_i32 s9, 0x26e0
	v_mad_i64_i32 v[10:11], s[16:17], v8, s9, v[6:7]
	global_load_dword v144, v[10:11], off
.LBB0_2771:
	s_or_b64 exec, exec, s[10:11]
	s_and_b64 vcc, exec, s[6:7]
	s_cbranch_vccnz .LBB0_2773
	v_ashrrev_i32_e32 v9, 31, v8
	v_lshl_add_u64 v[8:9], v[8:9], 2, v[2:3]
	global_load_dword v176, v[8:9], off
.LBB0_2773:
	v_mov_b32_e32 v145, 0
	v_or_b32_e32 v8, s8, v51
	s_and_saveexec_b64 s[10:11], s[4:5]
	s_cbranch_execz .LBB0_2775
	s_movk_i32 s9, 0x26e0
	v_mad_i64_i32 v[10:11], s[16:17], v8, s9, v[6:7]
	global_load_dword v145, v[10:11], off
.LBB0_2775:
	s_or_b64 exec, exec, s[10:11]
	s_and_b64 vcc, exec, s[6:7]
	s_cbranch_vccnz .LBB0_2777
	v_ashrrev_i32_e32 v9, 31, v8
	v_lshl_add_u64 v[8:9], v[8:9], 2, v[2:3]
	global_load_dword v177, v[8:9], off
.LBB0_2777:
	v_mov_b32_e32 v146, 0
	v_or_b32_e32 v8, s8, v52
	s_and_saveexec_b64 s[10:11], s[4:5]
	s_cbranch_execz .LBB0_2779
	s_movk_i32 s9, 0x26e0
	v_mad_i64_i32 v[10:11], s[16:17], v8, s9, v[6:7]
	global_load_dword v146, v[10:11], off
.LBB0_2779:
	s_or_b64 exec, exec, s[10:11]
	s_and_b64 vcc, exec, s[6:7]
	s_cbranch_vccnz .LBB0_2781
	v_ashrrev_i32_e32 v9, 31, v8
	v_lshl_add_u64 v[8:9], v[8:9], 2, v[2:3]
	global_load_dword v178, v[8:9], off
.LBB0_2781:
	v_mov_b32_e32 v147, 0
	v_or_b32_e32 v8, s8, v53
	s_and_saveexec_b64 s[10:11], s[4:5]
	s_cbranch_execz .LBB0_2783
	s_movk_i32 s9, 0x26e0
	v_mad_i64_i32 v[10:11], s[16:17], v8, s9, v[6:7]
	global_load_dword v147, v[10:11], off
.LBB0_2783:
	s_or_b64 exec, exec, s[10:11]
	s_and_b64 vcc, exec, s[6:7]
	s_cbranch_vccnz .LBB0_2785
	v_ashrrev_i32_e32 v9, 31, v8
	v_lshl_add_u64 v[8:9], v[8:9], 2, v[2:3]
	global_load_dword v179, v[8:9], off
.LBB0_2785:
	v_mov_b32_e32 v148, 0
	v_or_b32_e32 v8, s8, v54
	s_and_saveexec_b64 s[10:11], s[4:5]
	s_cbranch_execz .LBB0_2787
	s_movk_i32 s9, 0x26e0
	v_mad_i64_i32 v[10:11], s[16:17], v8, s9, v[6:7]
	global_load_dword v148, v[10:11], off
.LBB0_2787:
	s_or_b64 exec, exec, s[10:11]
	s_and_b64 vcc, exec, s[6:7]
	s_cbranch_vccnz .LBB0_2789
	v_ashrrev_i32_e32 v9, 31, v8
	v_lshl_add_u64 v[8:9], v[8:9], 2, v[2:3]
	global_load_dword v180, v[8:9], off
.LBB0_2789:
	v_mov_b32_e32 v149, 0
	v_or_b32_e32 v8, s8, v56
	s_and_saveexec_b64 s[10:11], s[4:5]
	s_cbranch_execz .LBB0_2791
	s_movk_i32 s9, 0x26e0
	v_mad_i64_i32 v[10:11], s[16:17], v8, s9, v[6:7]
	global_load_dword v149, v[10:11], off
.LBB0_2791:
	s_or_b64 exec, exec, s[10:11]
	s_and_b64 vcc, exec, s[6:7]
	s_cbranch_vccnz .LBB0_2793
	v_ashrrev_i32_e32 v9, 31, v8
	v_lshl_add_u64 v[8:9], v[8:9], 2, v[2:3]
	global_load_dword v181, v[8:9], off
.LBB0_2793:
	v_mov_b32_e32 v150, 0
	v_or_b32_e32 v8, s8, v57
	s_and_saveexec_b64 s[10:11], s[4:5]
	s_cbranch_execz .LBB0_2795
	s_movk_i32 s9, 0x26e0
	v_mad_i64_i32 v[10:11], s[16:17], v8, s9, v[6:7]
	global_load_dword v150, v[10:11], off
.LBB0_2795:
	s_or_b64 exec, exec, s[10:11]
	s_and_b64 vcc, exec, s[6:7]
	s_cbranch_vccnz .LBB0_2797
	v_ashrrev_i32_e32 v9, 31, v8
	v_lshl_add_u64 v[8:9], v[8:9], 2, v[2:3]
	global_load_dword v182, v[8:9], off
.LBB0_2797:
	v_mov_b32_e32 v151, 0
	v_or_b32_e32 v8, s8, v58
	s_and_saveexec_b64 s[10:11], s[4:5]
	s_cbranch_execz .LBB0_2799
	s_movk_i32 s9, 0x26e0
	v_mad_i64_i32 v[10:11], s[16:17], v8, s9, v[6:7]
	global_load_dword v151, v[10:11], off
.LBB0_2799:
	s_or_b64 exec, exec, s[10:11]
	s_and_b64 vcc, exec, s[6:7]
	s_cbranch_vccnz .LBB0_2801
	v_ashrrev_i32_e32 v9, 31, v8
	v_lshl_add_u64 v[8:9], v[8:9], 2, v[2:3]
	global_load_dword v183, v[8:9], off

; #define LDS_WAIT() asm volatile("s_waitcnt lgkmcnt(0)" ::: "memory")
; __device__ __forceinline__ void transpose_mat(const float* __restrict__ W, int K, int N, int Npad, bf16_t* __restrict__ WT, int blk_mul, int blk_off,
;                                               LAS float* scr, int gw, int NGW, int lane, const float* __restrict__ gk = nullptr) {
;     ...
;         const int ncol = n0 + (lane & 31);
; #pragma unroll
;         for (int i = 0; i < 32; ++i) { const int kk = 2 * i + (lane >> 5); float w = (ncol < N) ? W[(size_t)(k0 + kk) * N + ncol] : 0.f; if (gk) w *= gk[k0 + kk]; scr[kk * 33 + (lane & 31)] = w; }
;         LDS_WAIT();
.Ltp5_nomul_1:
	v_add_u32_e32 v8, v39, v40
	ds_write_b32 v8, v136
	v_add_u32_e32 v8, v39, v80
	ds_write_b32 v8, v137
	v_add_u32_e32 v8, v39, v81
	ds_write_b32 v8, v138
	v_add_u32_e32 v8, v39, v82
	ds_write_b32 v8, v139
	v_add_u32_e32 v8, v39, v45
	ds_write_b32 v8, v140
	v_add_u32_e32 v8, v39, v83
	ds_write_b32 v8, v141
	v_add_u32_e32 v8, v39, v84
	ds_write_b32 v8, v142
	v_add_u32_e32 v8, v39, v85
	ds_write_b32 v8, v143
	v_add_u32_e32 v8, v39, v50
	ds_write_b32 v8, v144
	v_add_u32_e32 v8, v39, v86
	ds_write_b32 v8, v145
	v_add_u32_e32 v8, v39, v87
	ds_write_b32 v8, v146
	v_add_u32_e32 v8, v39, v88
	ds_write_b32 v8, v147
	v_add_u32_e32 v8, v39, v55
	ds_write_b32 v8, v148
	v_add_u32_e32 v8, v39, v89
	ds_write_b32 v8, v149
	v_add_u32_e32 v8, v39, v90
	ds_write_b32 v8, v150
	v_add_u32_e32 v8, v39, v91
	ds_write_b32 v8, v151
	v_mov_b32_e32 v152, 0
	v_or_b32_e32 v8, s8, v59
	s_and_saveexec_b64 s[10:11], s[4:5]
	s_cbranch_execz .LBB0_2803
	s_movk_i32 s9, 0x26e0
	v_mad_i64_i32 v[10:11], s[16:17], v8, s9, v[6:7]
	global_load_dword v152, v[10:11], off
.LBB0_2803:
	s_or_b64 exec, exec, s[10:11]
	s_and_b64 vcc, exec, s[6:7]
	s_cbranch_vccnz .LBB0_2805
	v_ashrrev_i32_e32 v9, 31, v8
	v_lshl_add_u64 v[8:9], v[8:9], 2, v[2:3]
	global_load_dword v184, v[8:9], off
.LBB0_2805:
	v_mov_b32_e32 v153, 0
	v_or_b32_e32 v8, s8, v61
	s_and_saveexec_b64 s[10:11], s[4:5]
	s_cbranch_execz .LBB0_2807
	s_movk_i32 s9, 0x26e0
	v_mad_i64_i32 v[10:11], s[16:17], v8, s9, v[6:7]
	global_load_dword v153, v[10:11], off
.LBB0_2807:
	s_or_b64 exec, exec, s[10:11]
	s_and_b64 vcc, exec, s[6:7]
	s_cbranch_vccnz .LBB0_2809
	v_ashrrev_i32_e32 v9, 31, v8
	v_lshl_add_u64 v[8:9], v[8:9], 2, v[2:3]
	global_load_dword v185, v[8:9], off
.LBB0_2809:
	v_mov_b32_e32 v154, 0
	v_or_b32_e32 v8, s8, v62
	s_and_saveexec_b64 s[10:11], s[4:5]
	s_cbranch_execz .LBB0_2811
	s_movk_i32 s9, 0x26e0
	v_mad_i64_i32 v[10:11], s[16:17], v8, s9, v[6:7]
	global_load_dword v154, v[10:11], off
.LBB0_2811:
	s_or_b64 exec, exec, s[10:11]
	s_and_b64 vcc, exec, s[6:7]
	s_cbranch_vccnz .LBB0_2813
	v_ashrrev_i32_e32 v9, 31, v8
	v_lshl_add_u64 v[8:9], v[8:9], 2, v[2:3]
	global_load_dword v186, v[8:9], off
.LBB0_2813:
	v_mov_b32_e32 v155, 0
	v_or_b32_e32 v8, s8, v63
	s_and_saveexec_b64 s[10:11], s[4:5]
	s_cbranch_execz .LBB0_2815
	s_movk_i32 s9, 0x26e0
	v_mad_i64_i32 v[10:11], s[16:17], v8, s9, v[6:7]
	global_load_dword v155, v[10:11], off
.LBB0_2815:
	s_or_b64 exec, exec, s[10:11]
	s_and_b64 vcc, exec, s[6:7]
	s_cbranch_vccnz .LBB0_2817
	v_ashrrev_i32_e32 v9, 31, v8
	v_lshl_add_u64 v[8:9], v[8:9], 2, v[2:3]
	global_load_dword v187, v[8:9], off
.LBB0_2817:
	v_mov_b32_e32 v156, 0
	v_or_b32_e32 v8, s8, v64
	s_and_saveexec_b64 s[10:11], s[4:5]
	s_cbranch_execz .LBB0_2819
	s_movk_i32 s9, 0x26e0
	v_mad_i64_i32 v[10:11], s[16:17], v8, s9, v[6:7]
	global_load_dword v156, v[10:11], off
.LBB0_2819:
	s_or_b64 exec, exec, s[10:11]
	s_and_b64 vcc, exec, s[6:7]
	s_cbranch_vccnz .LBB0_2821
	v_ashrrev_i32_e32 v9, 31, v8
	v_lshl_add_u64 v[8:9], v[8:9], 2, v[2:3]
	global_load_dword v188, v[8:9], off
.LBB0_2821:
	v_mov_b32_e32 v157, 0
	v_or_b32_e32 v8, s8, v66
	s_and_saveexec_b64 s[10:11], s[4:5]
	s_cbranch_execz .LBB0_2823
	s_movk_i32 s9, 0x26e0
	v_mad_i64_i32 v[10:11], s[16:17], v8, s9, v[6:7]
	global_load_dword v157, v[10:11], off
.LBB0_2823:
	s_or_b64 exec, exec, s[10:11]
	s_and_b64 vcc, exec, s[6:7]
	s_cbranch_vccnz .LBB0_2825
	v_ashrrev_i32_e32 v9, 31, v8
	v_lshl_add_u64 v[8:9], v[8:9], 2, v[2:3]
	global_load_dword v189, v[8:9], off
.LBB0_2825:
	v_mov_b32_e32 v158, 0
	v_or_b32_e32 v8, s8, v67
	s_and_saveexec_b64 s[10:11], s[4:5]
	s_cbranch_execz .LBB0_2827
	s_movk_i32 s9, 0x26e0
	v_mad_i64_i32 v[10:11], s[16:17], v8, s9, v[6:7]
	global_load_dword v158, v[10:11], off
.LBB0_2827:
	s_or_b64 exec, exec, s[10:11]
	s_and_b64 vcc, exec, s[6:7]
	s_cbranch_vccnz .LBB0_2829
	v_ashrrev_i32_e32 v9, 31, v8
	v_lshl_add_u64 v[8:9], v[8:9], 2, v[2:3]
	global_load_dword v190, v[8:9], off
.LBB0_2829:
	v_mov_b32_e32 v159, 0
	v_or_b32_e32 v8, s8, v68
	s_and_saveexec_b64 s[10:11], s[4:5]
	s_cbranch_execz .LBB0_2831
	s_movk_i32 s9, 0x26e0
	v_mad_i64_i32 v[10:11], s[16:17], v8, s9, v[6:7]
	global_load_dword v159, v[10:11], off
.LBB0_2831:
	s_or_b64 exec, exec, s[10:11]
	s_and_b64 vcc, exec, s[6:7]
	s_cbranch_vccnz .LBB0_2833
	v_ashrrev_i32_e32 v9, 31, v8
	v_lshl_add_u64 v[8:9], v[8:9], 2, v[2:3]
	global_load_dword v191, v[8:9], off
.LBB0_2833:
	v_mov_b32_e32 v160, 0
	v_or_b32_e32 v8, s8, v69
	s_and_saveexec_b64 s[10:11], s[4:5]
	s_cbranch_execz .LBB0_2835
	s_movk_i32 s9, 0x26e0
	v_mad_i64_i32 v[10:11], s[16:17], v8, s9, v[6:7]
	global_load_dword v160, v[10:11], off
; #define LDS_WAIT() asm volatile("s_waitcnt lgkmcnt(0)" ::: "memory")
; __device__ __forceinline__ void transpose_mat(const float* __restrict__ W, int K, int N, int Npad, bf16_t* __restrict__ WT, int blk_mul, int blk_off,
;                                               LAS float* scr, int gw, int NGW, int lane, const float* __restrict__ gk = nullptr) {
;     ...
;         const int ncol = n0 + (lane & 31);
; #pragma unroll
;         for (int i = 0; i < 32; ++i) { const int kk = 2 * i + (lane >> 5); float w = (ncol < N) ? W[(size_t)(k0 + kk) * N + ncol] : 0.f; if (gk) w *= gk[k0 + kk]; scr[kk * 33 + (lane & 31)] = w; }
;         LDS_WAIT();
.LBB0_2835:
	s_or_b64 exec, exec, s[10:11]
	s_and_b64 vcc, exec, s[6:7]
	s_cbranch_vccnz .LBB0_2837
	v_ashrrev_i32_e32 v9, 31, v8
	v_lshl_add_u64 v[8:9], v[8:9], 2, v[2:3]
	global_load_dword v192, v[8:9], off
.LBB0_2837:
	v_mov_b32_e32 v161, 0
	v_or_b32_e32 v8, s8, v71
	s_and_saveexec_b64 s[10:11], s[4:5]
	s_cbranch_execz .LBB0_2839
	s_movk_i32 s9, 0x26e0
	v_mad_i64_i32 v[10:11], s[16:17], v8, s9, v[6:7]
	global_load_dword v161, v[10:11], off
.LBB0_2839:
	s_or_b64 exec, exec, s[10:11]
	s_and_b64 vcc, exec, s[6:7]
	s_cbranch_vccnz .LBB0_2841
	v_ashrrev_i32_e32 v9, 31, v8
	v_lshl_add_u64 v[8:9], v[8:9], 2, v[2:3]
	global_load_dword v193, v[8:9], off
.LBB0_2841:
	v_mov_b32_e32 v162, 0
	v_or_b32_e32 v8, s8, v72
	s_and_saveexec_b64 s[10:11], s[4:5]
	s_cbranch_execz .LBB0_2843
	s_movk_i32 s9, 0x26e0
	v_mad_i64_i32 v[10:11], s[16:17], v8, s9, v[6:7]
	global_load_dword v162, v[10:11], off
.LBB0_2843:
	s_or_b64 exec, exec, s[10:11]
	s_and_b64 vcc, exec, s[6:7]
	s_cbranch_vccnz .LBB0_2845
	v_ashrrev_i32_e32 v9, 31, v8
	v_lshl_add_u64 v[8:9], v[8:9], 2, v[2:3]
	global_load_dword v194, v[8:9], off
.LBB0_2845:
	v_mov_b32_e32 v163, 0
	v_or_b32_e32 v8, s8, v75
	s_and_saveexec_b64 s[10:11], s[4:5]
	s_cbranch_execz .LBB0_2847
	s_movk_i32 s9, 0x26e0
	v_mad_i64_i32 v[26:27], s[16:17], v8, s9, v[6:7]
	global_load_dword v163, v[26:27], off
.LBB0_2847:
	s_or_b64 exec, exec, s[10:11]
	s_and_b64 vcc, exec, s[6:7]
	s_cbranch_vccnz .LBB0_2849
	v_ashrrev_i32_e32 v9, 31, v8
	v_lshl_add_u64 v[8:9], v[8:9], 2, v[2:3]
	global_load_dword v195, v[8:9], off
.LBB0_2849:
	v_mov_b32_e32 v164, 0
	v_or_b32_e32 v8, s8, v76
	s_and_saveexec_b64 s[10:11], s[4:5]
	s_cbranch_execz .LBB0_2851
	s_movk_i32 s9, 0x26e0
	v_mad_i64_i32 v[26:27], s[16:17], v8, s9, v[6:7]
	global_load_dword v164, v[26:27], off
.LBB0_2851:
	s_or_b64 exec, exec, s[10:11]
	s_and_b64 vcc, exec, s[6:7]
	s_cbranch_vccnz .LBB0_2853
	v_ashrrev_i32_e32 v9, 31, v8
	v_lshl_add_u64 v[8:9], v[8:9], 2, v[2:3]
	global_load_dword v196, v[8:9], off
.LBB0_2853:
	v_mov_b32_e32 v165, 0
	v_or_b32_e32 v8, s8, v77
	s_and_saveexec_b64 s[10:11], s[4:5]
	s_cbranch_execz .LBB0_2855
	s_movk_i32 s9, 0x26e0
	v_mad_i64_i32 v[26:27], s[16:17], v8, s9, v[6:7]
	global_load_dword v165, v[26:27], off
.LBB0_2855:
	s_or_b64 exec, exec, s[10:11]
	s_and_b64 vcc, exec, s[6:7]
	s_cbranch_vccnz .LBB0_2857
	v_ashrrev_i32_e32 v9, 31, v8
	v_lshl_add_u64 v[8:9], v[8:9], 2, v[2:3]
	global_load_dword v197, v[8:9], off
.LBB0_2857:
	v_mov_b32_e32 v166, 0
	v_or_b32_e32 v8, s8, v78
	s_and_saveexec_b64 s[10:11], s[4:5]
	s_cbranch_execz .LBB0_2859
	s_movk_i32 s9, 0x26e0
	v_mad_i64_i32 v[26:27], s[16:17], v8, s9, v[6:7]
	global_load_dword v166, v[26:27], off
.LBB0_2859:
	s_or_b64 exec, exec, s[10:11]
	s_and_b64 vcc, exec, s[6:7]
	s_cbranch_vccnz .LBB0_2861
	v_ashrrev_i32_e32 v9, 31, v8
	v_lshl_add_u64 v[8:9], v[8:9], 2, v[2:3]
	global_load_dword v198, v[8:9], off
.LBB0_2861:
	v_mov_b32_e32 v167, 0
	v_or_b32_e32 v8, s8, v79
	s_and_saveexec_b64 s[10:11], s[4:5]
	s_cbranch_execz .LBB0_2863
	s_movk_i32 s4, 0x26e0
	v_mad_i64_i32 v[6:7], s[4:5], v8, s4, v[6:7]
	global_load_dword v167, v[6:7], off
.LBB0_2863:
	s_or_b64 exec, exec, s[10:11]
	s_and_b64 vcc, exec, s[6:7]
	s_cbranch_vccnz .Ltp5_join
	v_ashrrev_i32_e32 v9, 31, v8
	v_lshl_add_u64 v[6:7], v[8:9], 2, v[2:3]
	global_load_dword v199, v[6:7], off
.Ltp5_join:
	s_waitcnt vmcnt(0)
	s_and_b64 vcc, exec, s[6:7]
	s_cbranch_vccnz .Ltp5_nomul_2
	v_mul_f32_e32 v152, v152, v184
	v_mul_f32_e32 v153, v153, v185
	v_mul_f32_e32 v154, v154, v186
	v_mul_f32_e32 v155, v155, v187
	v_mul_f32_e32 v156, v156, v188
	v_mul_f32_e32 v157, v157, v189
	v_mul_f32_e32 v158, v158, v190
	v_mul_f32_e32 v159, v159, v191
	v_mul_f32_e32 v160, v160, v192
	v_mul_f32_e32 v161, v161, v193
	v_mul_f32_e32 v162, v162, v194
	v_mul_f32_e32 v163, v163, v195
	v_mul_f32_e32 v164, v164, v196
	v_mul_f32_e32 v165, v165, v197
	v_mul_f32_e32 v166, v166, v198
	v_mul_f32_e32 v167, v167, v199
.Ltp5_nomul_2:
	v_add_u32_e32 v8, v39, v60
	ds_write_b32 v8, v152
	v_add_u32_e32 v8, v39, v92
	ds_write_b32 v8, v153
	v_add_u32_e32 v8, v39, v93
	ds_write_b32 v8, v154
	v_add_u32_e32 v8, v39, v94
	ds_write_b32 v8, v155
	v_add_u32_e32 v8, v39, v65
	ds_write_b32 v8, v156
	v_add_u32_e32 v8, v39, v95
	ds_write_b32 v8, v157
	v_add_u32_e32 v8, v39, v96
	ds_write_b32 v8, v158
	v_add_u32_e32 v8, v39, v97
	ds_write_b32 v8, v159
	v_add_u32_e32 v8, v39, v70
	ds_write_b32 v8, v160
	v_add_u32_e32 v8, v39, v98
	ds_write_b32 v8, v161
	v_add_u32_e32 v10, v39, v73
	ds_write_b32 v10, v162
	ds_write_b32 v10, v163 offset:264
	ds_write_b32 v10, v164 offset:528
	ds_write_b32 v10, v165 offset:792
	ds_write_b32 v10, v166 offset:1056
	v_mov_b32_e32 v11, v167
	s_branch .LBB0_2736
